# v15 + the 17 GEMM inner-loop heads aligned to 64 bytes (.p2align 6)
# baseline (speedup 1.0000x reference)
; template <class Epi, class Sched, bool ALIGN_EPI = false, bool SP2 = false>
; __device__ __forceinline__ void gemm_phase(PG8_LAS unsigned char* lds, const Gemm g, const Sched& S, const Epi& E) {
;     ...
;         const bool has_next = S.next(ui + 1, nxt);
;         const char* nA = has_next ? (const char*)g.A + (size_t)nxt.pm * tstepA : cA; const char* nB = has_next ? (const char*)g.Bt + (size_t)nxt.pn * tstepB : cB;
;         for (int t = 0; t < nt; t += 2) {
;             const bool last = (t == nt - 2);
;             const char* a1 = cA + (size_t)(t + 1) * kstep;
;             const char* a2 = last ? nA : cA + (size_t)(t + 2) * kstep; const char* b2 = last ? nB : cB + (size_t)(t + 2) * kstep;
;             const char* a3 = a2 + kstep; const char* b3 = b2 + kstep;
;     ...
; #pragma unroll
;         for (int a = 0; a < 2; ++a)
; #pragma unroll
;             for (int b = 0; b < 2; ++b)
; #pragma unroll
;                 for (int m = 0; m < 4; ++m)
; #pragma unroll
;                     for (int n = 0; n < 2; ++n) acc[a][b][m][n] = (f32x4){0.f, 0.f, 0.f, 0.f};
.LBB0_184:
	s_ashr_i32 s27, s26, 31
	s_lshl_b64 s[28:29], s[26:27], 20
	s_add_u32 s28, s86, s28
	s_addc_u32 s29, s87, s29
	s_and_b64 s[30:31], s[8:9], exec
	s_cselect_b32 s1, s29, s35
	s_cselect_b32 s11, s28, s34
	s_ashr_i32 s25, s24, 31
	s_lshl_b64 s[30:31], s[24:25], 20
	s_add_u32 s30, s64, s30
	s_addc_u32 s31, s65, s31
	s_and_b64 s[38:39], s[8:9], exec
	s_cselect_b32 s25, s31, s37
	s_cselect_b32 s27, s30, s36
	s_add_u32 s34, s34, 0x80080
	s_addc_u32 s35, s35, 0
	s_add_u32 s40, s36, 0x100
	v_mov_b32_e32 v2, 0
	s_addc_u32 s41, s37, 0
	s_mov_b32 s42, -2
	v_mov_b32_e32 v3, v2
	v_mov_b32_e32 v4, v2
	v_mov_b32_e32 v5, v2
	v_mov_b32_e32 v6, v2
	v_mov_b32_e32 v7, v2
	v_mov_b32_e32 v8, v2
	v_mov_b32_e32 v9, v2
	v_mov_b32_e32 v18, v2
	v_mov_b32_e32 v19, v2
	v_mov_b32_e32 v20, v2
	v_mov_b32_e32 v21, v2
	v_mov_b32_e32 v22, v2
	v_mov_b32_e32 v23, v2
	v_mov_b32_e32 v24, v2
	v_mov_b32_e32 v25, v2
	v_mov_b32_e32 v34, v2
	v_mov_b32_e32 v35, v2
	v_mov_b32_e32 v36, v2
	v_mov_b32_e32 v37, v2
	v_mov_b32_e32 v38, v2
	v_mov_b32_e32 v39, v2
	v_mov_b32_e32 v40, v2
	v_mov_b32_e32 v41, v2
	v_mov_b32_e32 v50, v2
	v_mov_b32_e32 v51, v2
	v_mov_b32_e32 v52, v2
	v_mov_b32_e32 v53, v2
	v_mov_b32_e32 v54, v2
	v_mov_b32_e32 v55, v2
	v_mov_b32_e32 v56, v2
	v_mov_b32_e32 v57, v2
	v_mov_b32_e32 v10, v2
	v_mov_b32_e32 v11, v2
	v_mov_b32_e32 v12, v2
	v_mov_b32_e32 v13, v2
	v_mov_b32_e32 v14, v2
	v_mov_b32_e32 v15, v2
	v_mov_b32_e32 v16, v2
	v_mov_b32_e32 v17, v2
	v_mov_b32_e32 v26, v2
	v_mov_b32_e32 v27, v2
	v_mov_b32_e32 v28, v2
	v_mov_b32_e32 v29, v2
	v_mov_b32_e32 v30, v2
	v_mov_b32_e32 v31, v2
	v_mov_b32_e32 v32, v2
	v_mov_b32_e32 v33, v2
	v_mov_b32_e32 v42, v2
	v_mov_b32_e32 v43, v2
	v_mov_b32_e32 v44, v2
	v_mov_b32_e32 v45, v2
	v_mov_b32_e32 v46, v2
	v_mov_b32_e32 v47, v2
	v_mov_b32_e32 v48, v2
	v_mov_b32_e32 v49, v2
	v_mov_b32_e32 v58, v2
	v_mov_b32_e32 v59, v2
	v_mov_b32_e32 v60, v2
	v_mov_b32_e32 v61, v2
	v_mov_b32_e32 v62, v2
	v_mov_b32_e32 v63, v2
	v_mov_b32_e32 v64, v2
	v_mov_b32_e32 v65, v2
	v_mov_b32_e32 v66, v2
	v_mov_b32_e32 v67, v2
	v_mov_b32_e32 v68, v2
	v_mov_b32_e32 v69, v2
	v_mov_b32_e32 v70, v2
	v_mov_b32_e32 v71, v2
	v_mov_b32_e32 v72, v2
	v_mov_b32_e32 v73, v2
	v_mov_b32_e32 v82, v2
	v_mov_b32_e32 v83, v2
	v_mov_b32_e32 v84, v2
	v_mov_b32_e32 v85, v2
	v_mov_b32_e32 v86, v2
	v_mov_b32_e32 v87, v2
	v_mov_b32_e32 v88, v2
	v_mov_b32_e32 v89, v2
	v_mov_b32_e32 v98, v2
	v_mov_b32_e32 v99, v2
	v_mov_b32_e32 v100, v2
	v_mov_b32_e32 v101, v2
	v_mov_b32_e32 v102, v2
	v_mov_b32_e32 v103, v2
	v_mov_b32_e32 v104, v2
	v_mov_b32_e32 v105, v2
	v_mov_b32_e32 v114, v2
	v_mov_b32_e32 v115, v2
	v_mov_b32_e32 v116, v2
	v_mov_b32_e32 v117, v2
	v_mov_b32_e32 v118, v2
	v_mov_b32_e32 v119, v2
	v_mov_b32_e32 v120, v2
	v_mov_b32_e32 v121, v2
	v_mov_b32_e32 v74, v2
	v_mov_b32_e32 v75, v2
	v_mov_b32_e32 v76, v2
	v_mov_b32_e32 v77, v2
	v_mov_b32_e32 v78, v2
	v_mov_b32_e32 v79, v2
	v_mov_b32_e32 v80, v2
	v_mov_b32_e32 v81, v2
	v_mov_b32_e32 v90, v2
	v_mov_b32_e32 v91, v2
	v_mov_b32_e32 v92, v2
	v_mov_b32_e32 v93, v2
	v_mov_b32_e32 v94, v2
	v_mov_b32_e32 v95, v2
	v_mov_b32_e32 v96, v2
	v_mov_b32_e32 v97, v2
	v_mov_b32_e32 v106, v2
	v_mov_b32_e32 v107, v2
	v_mov_b32_e32 v108, v2
	v_mov_b32_e32 v109, v2
	v_mov_b32_e32 v110, v2
	v_mov_b32_e32 v111, v2
	v_mov_b32_e32 v112, v2
	v_mov_b32_e32 v113, v2
	v_mov_b32_e32 v122, v2
	v_mov_b32_e32 v123, v2
	v_mov_b32_e32 v124, v2
	v_mov_b32_e32 v125, v2
	v_mov_b32_e32 v126, v2
	v_mov_b32_e32 v127, v2
	v_mov_b32_e32 v128, v2
	v_mov_b32_e32 v129, v2
	.p2align 6

; template <class Epi, class Sched, bool ALIGN_EPI = false, bool SP2 = false>
; __device__ __forceinline__ void gemm_phase(PG8_LAS unsigned char* lds, const Gemm g, const Sched& S, const Epi& E) {
;     ...
;         const bool has_next = S.next(ui + 1, nxt);
;         const char* nA = has_next ? (const char*)g.A + (size_t)nxt.pm * tstepA : cA; const char* nB = has_next ? (const char*)g.Bt + (size_t)nxt.pn * tstepB : cB;
;         for (int t = 0; t < nt; t += 2) {
;             const bool last = (t == nt - 2);
;             const char* a1 = cA + (size_t)(t + 1) * kstep;
;             const char* a2 = last ? nA : cA + (size_t)(t + 2) * kstep; const char* b2 = last ? nB : cB + (size_t)(t + 2) * kstep;
;             const char* a3 = a2 + kstep; const char* b3 = b2 + kstep;
;     ...
; #pragma unroll
;         for (int a = 0; a < 2; ++a)
; #pragma unroll
;             for (int b = 0; b < 2; ++b)
; #pragma unroll
;                 for (int m = 0; m < 4; ++m)
; #pragma unroll
;                     for (int n = 0; n < 2; ++n) acc[a][b][m][n] = (f32x4){0.f, 0.f, 0.f, 0.f};
.LBB0_801:
	s_ashr_i32 s31, s30, 31
	s_lshl_b64 s[34:35], s[30:31], 20
	s_add_u32 s34, s6, s34
	s_addc_u32 s35, s7, s35
	s_and_b64 s[36:37], s[4:5], exec
	s_cselect_b32 s31, s35, s39
	s_cselect_b32 s61, s34, s38
	s_ashr_i32 s29, s28, 31
	s_lshl_b64 s[36:37], s[28:29], 20
	s_add_u32 s36, s88, s36
	s_addc_u32 s37, s89, s37
	s_and_b64 s[42:43], s[4:5], exec
	s_cselect_b32 s29, s37, s41
	s_cselect_b32 s62, s36, s40
	s_add_u32 s38, s38, 0x80080
	s_addc_u32 s39, s39, 0
	s_add_u32 s63, s40, 0x100
	v_mov_b32_e32 v2, 0
	s_addc_u32 s64, s41, 0
	s_mov_b32 s65, -2
	v_mov_b32_e32 v3, v2
	v_mov_b32_e32 v4, v2
	v_mov_b32_e32 v5, v2
	v_mov_b32_e32 v6, v2
	v_mov_b32_e32 v7, v2
	v_mov_b32_e32 v8, v2
	v_mov_b32_e32 v9, v2
	v_mov_b32_e32 v10, v2
	v_mov_b32_e32 v11, v2
	v_mov_b32_e32 v12, v2
	v_mov_b32_e32 v13, v2
	v_mov_b32_e32 v14, v2
	v_mov_b32_e32 v15, v2
	v_mov_b32_e32 v16, v2
	v_mov_b32_e32 v17, v2
	v_mov_b32_e32 v26, v2
	v_mov_b32_e32 v27, v2
	v_mov_b32_e32 v28, v2
	v_mov_b32_e32 v29, v2
	v_mov_b32_e32 v30, v2
	v_mov_b32_e32 v31, v2
	v_mov_b32_e32 v32, v2
	v_mov_b32_e32 v33, v2
	v_mov_b32_e32 v42, v2
	v_mov_b32_e32 v43, v2
	v_mov_b32_e32 v44, v2
	v_mov_b32_e32 v45, v2
	v_mov_b32_e32 v46, v2
	v_mov_b32_e32 v47, v2
	v_mov_b32_e32 v48, v2
	v_mov_b32_e32 v49, v2
	v_mov_b32_e32 v18, v2
	v_mov_b32_e32 v19, v2
	v_mov_b32_e32 v20, v2
	v_mov_b32_e32 v21, v2
	v_mov_b32_e32 v22, v2
	v_mov_b32_e32 v23, v2
	v_mov_b32_e32 v24, v2
	v_mov_b32_e32 v25, v2
	v_mov_b32_e32 v34, v2
	v_mov_b32_e32 v35, v2
	v_mov_b32_e32 v36, v2
	v_mov_b32_e32 v37, v2
	v_mov_b32_e32 v38, v2
	v_mov_b32_e32 v39, v2
	v_mov_b32_e32 v40, v2
	v_mov_b32_e32 v41, v2
	v_mov_b32_e32 v50, v2
	v_mov_b32_e32 v51, v2
	v_mov_b32_e32 v52, v2
	v_mov_b32_e32 v53, v2
	v_mov_b32_e32 v54, v2
	v_mov_b32_e32 v55, v2
	v_mov_b32_e32 v56, v2
	v_mov_b32_e32 v57, v2
	v_mov_b32_e32 v58, v2
	v_mov_b32_e32 v59, v2
	v_mov_b32_e32 v60, v2
	v_mov_b32_e32 v61, v2
	v_mov_b32_e32 v62, v2
	v_mov_b32_e32 v63, v2
	v_mov_b32_e32 v64, v2
	v_mov_b32_e32 v65, v2
	v_mov_b32_e32 v66, v2
	v_mov_b32_e32 v67, v2
	v_mov_b32_e32 v68, v2
	v_mov_b32_e32 v69, v2
	v_mov_b32_e32 v70, v2
	v_mov_b32_e32 v71, v2
	v_mov_b32_e32 v72, v2
	v_mov_b32_e32 v73, v2
	v_mov_b32_e32 v74, v2
	v_mov_b32_e32 v75, v2
	v_mov_b32_e32 v76, v2
	v_mov_b32_e32 v77, v2
	v_mov_b32_e32 v78, v2
	v_mov_b32_e32 v79, v2
	v_mov_b32_e32 v80, v2
	v_mov_b32_e32 v81, v2
	v_mov_b32_e32 v90, v2
	v_mov_b32_e32 v91, v2
	v_mov_b32_e32 v92, v2
	v_mov_b32_e32 v93, v2
	v_mov_b32_e32 v94, v2
	v_mov_b32_e32 v95, v2
	v_mov_b32_e32 v96, v2
	v_mov_b32_e32 v97, v2
	v_mov_b32_e32 v106, v2
	v_mov_b32_e32 v107, v2
	v_mov_b32_e32 v108, v2
	v_mov_b32_e32 v109, v2
	v_mov_b32_e32 v110, v2
	v_mov_b32_e32 v111, v2
	v_mov_b32_e32 v112, v2
	v_mov_b32_e32 v113, v2
	v_mov_b32_e32 v82, v2
	v_mov_b32_e32 v83, v2
	v_mov_b32_e32 v84, v2
	v_mov_b32_e32 v85, v2
	v_mov_b32_e32 v86, v2
	v_mov_b32_e32 v87, v2
	v_mov_b32_e32 v88, v2
	v_mov_b32_e32 v89, v2
	v_mov_b32_e32 v98, v2
	v_mov_b32_e32 v99, v2
	v_mov_b32_e32 v100, v2
	v_mov_b32_e32 v101, v2
	v_mov_b32_e32 v102, v2
	v_mov_b32_e32 v103, v2
	v_mov_b32_e32 v104, v2
	v_mov_b32_e32 v105, v2
	v_mov_b32_e32 v114, v2
	v_mov_b32_e32 v115, v2
	v_mov_b32_e32 v116, v2
	v_mov_b32_e32 v117, v2
	v_mov_b32_e32 v118, v2
	v_mov_b32_e32 v119, v2
	v_mov_b32_e32 v120, v2
	v_mov_b32_e32 v121, v2
	v_mov_b32_e32 v122, v2
	v_mov_b32_e32 v123, v2
	v_mov_b32_e32 v124, v2
	v_mov_b32_e32 v125, v2
	v_mov_b32_e32 v126, v2
	v_mov_b32_e32 v127, v2
	v_mov_b32_e32 v128, v2
	v_mov_b32_e32 v129, v2
	.p2align 6

; template <class Epi, class Sched, bool ALIGN_EPI = false, bool SP2 = false>
; __device__ __forceinline__ void gemm_phase(PG8_LAS unsigned char* lds, const Gemm g, const Sched& S, const Epi& E) {
;     ...
;         const bool has_next = S.next(ui + 1, nxt);
;         const char* nA = has_next ? (const char*)g.A + (size_t)nxt.pm * tstepA : cA; const char* nB = has_next ? (const char*)g.Bt + (size_t)nxt.pn * tstepB : cB;
;         for (int t = 0; t < nt; t += 2) {
;             const bool last = (t == nt - 2);
;             const char* a1 = cA + (size_t)(t + 1) * kstep;
;             const char* a2 = last ? nA : cA + (size_t)(t + 2) * kstep; const char* b2 = last ? nB : cB + (size_t)(t + 2) * kstep;
;             const char* a3 = a2 + kstep; const char* b3 = b2 + kstep;
;     ...
; #pragma unroll
;         for (int a = 0; a < 2; ++a)
; #pragma unroll
;             for (int b = 0; b < 2; ++b)
; #pragma unroll
;                 for (int m = 0; m < 4; ++m)
; #pragma unroll
;                     for (int n = 0; n < 2; ++n) acc[a][b][m][n] = (f32x4){0.f, 0.f, 0.f, 0.f};
.LBB0_939:
	s_ashr_i32 s13, s12, 31
	s_lshl_b64 s[14:15], s[12:13], 20
	s_add_u32 s14, s86, s14
	s_addc_u32 s15, s87, s15
	s_and_b64 s[16:17], s[4:5], exec
	s_cselect_b32 s13, s15, s27
	s_cselect_b32 s48, s14, s26
	s_ashr_i32 s11, s10, 31
	s_lshl_b64 s[16:17], s[10:11], 20
	v_readlane_b32 s30, v254, 0
	v_readlane_b32 s31, v254, 1
	s_add_u32 s16, s30, s16
	s_addc_u32 s17, s31, s17
	s_and_b64 s[30:31], s[4:5], exec
	s_cselect_b32 s11, s17, s29
	s_cselect_b32 s49, s16, s28
	s_add_u32 s26, s26, 0x80080
	s_addc_u32 s27, s27, 0
	s_add_u32 s50, s28, 0x100
	v_mov_b32_e32 v2, 0
	s_addc_u32 s51, s29, 0
	s_mov_b32 s52, -2
	v_mov_b32_e32 v3, v2
	v_mov_b32_e32 v4, v2
	v_mov_b32_e32 v5, v2
	v_mov_b32_e32 v6, v2
	v_mov_b32_e32 v7, v2
	v_mov_b32_e32 v8, v2
	v_mov_b32_e32 v9, v2
	v_mov_b32_e32 v18, v2
	v_mov_b32_e32 v19, v2
	v_mov_b32_e32 v20, v2
	v_mov_b32_e32 v21, v2
	v_mov_b32_e32 v22, v2
	v_mov_b32_e32 v23, v2
	v_mov_b32_e32 v24, v2
	v_mov_b32_e32 v25, v2
	v_mov_b32_e32 v34, v2
	v_mov_b32_e32 v35, v2
	v_mov_b32_e32 v36, v2
	v_mov_b32_e32 v37, v2
	v_mov_b32_e32 v38, v2
	v_mov_b32_e32 v39, v2
	v_mov_b32_e32 v40, v2
	v_mov_b32_e32 v41, v2
	v_mov_b32_e32 v50, v2
	v_mov_b32_e32 v51, v2
	v_mov_b32_e32 v52, v2
	v_mov_b32_e32 v53, v2
	v_mov_b32_e32 v54, v2
	v_mov_b32_e32 v55, v2
	v_mov_b32_e32 v56, v2
	v_mov_b32_e32 v57, v2
	v_mov_b32_e32 v10, v2
	v_mov_b32_e32 v11, v2
	v_mov_b32_e32 v12, v2
	v_mov_b32_e32 v13, v2
	v_mov_b32_e32 v14, v2
	v_mov_b32_e32 v15, v2
	v_mov_b32_e32 v16, v2
	v_mov_b32_e32 v17, v2
	v_mov_b32_e32 v26, v2
	v_mov_b32_e32 v27, v2
	v_mov_b32_e32 v28, v2
	v_mov_b32_e32 v29, v2
	v_mov_b32_e32 v30, v2
	v_mov_b32_e32 v31, v2
	v_mov_b32_e32 v32, v2
	v_mov_b32_e32 v33, v2
	v_mov_b32_e32 v42, v2
	v_mov_b32_e32 v43, v2
	v_mov_b32_e32 v44, v2
	v_mov_b32_e32 v45, v2
	v_mov_b32_e32 v46, v2
	v_mov_b32_e32 v47, v2
	v_mov_b32_e32 v48, v2
	v_mov_b32_e32 v49, v2
	v_mov_b32_e32 v58, v2
	v_mov_b32_e32 v59, v2
	v_mov_b32_e32 v60, v2
	v_mov_b32_e32 v61, v2
	v_mov_b32_e32 v62, v2
	v_mov_b32_e32 v63, v2
	v_mov_b32_e32 v64, v2
	v_mov_b32_e32 v65, v2
	v_mov_b32_e32 v66, v2
	v_mov_b32_e32 v67, v2
	v_mov_b32_e32 v68, v2
	v_mov_b32_e32 v69, v2
	v_mov_b32_e32 v70, v2
	v_mov_b32_e32 v71, v2
	v_mov_b32_e32 v72, v2
	v_mov_b32_e32 v73, v2
	v_mov_b32_e32 v82, v2
	v_mov_b32_e32 v83, v2
	v_mov_b32_e32 v84, v2
	v_mov_b32_e32 v85, v2
	v_mov_b32_e32 v86, v2
	v_mov_b32_e32 v87, v2
	v_mov_b32_e32 v88, v2
	v_mov_b32_e32 v89, v2
	v_mov_b32_e32 v98, v2
	v_mov_b32_e32 v99, v2
	v_mov_b32_e32 v100, v2
	v_mov_b32_e32 v101, v2
	v_mov_b32_e32 v102, v2
	v_mov_b32_e32 v103, v2
	v_mov_b32_e32 v104, v2
	v_mov_b32_e32 v105, v2
	v_mov_b32_e32 v114, v2
	v_mov_b32_e32 v115, v2
	v_mov_b32_e32 v116, v2
	v_mov_b32_e32 v117, v2
	v_mov_b32_e32 v118, v2
	v_mov_b32_e32 v119, v2
	v_mov_b32_e32 v120, v2
	v_mov_b32_e32 v121, v2
	v_mov_b32_e32 v74, v2
	v_mov_b32_e32 v75, v2
	v_mov_b32_e32 v76, v2
	v_mov_b32_e32 v77, v2
	v_mov_b32_e32 v78, v2
	v_mov_b32_e32 v79, v2
	v_mov_b32_e32 v80, v2
	v_mov_b32_e32 v81, v2
	v_mov_b32_e32 v90, v2
	v_mov_b32_e32 v91, v2
	v_mov_b32_e32 v92, v2
	v_mov_b32_e32 v93, v2
	v_mov_b32_e32 v94, v2
	v_mov_b32_e32 v95, v2
	v_mov_b32_e32 v96, v2
	v_mov_b32_e32 v97, v2
	v_mov_b32_e32 v106, v2
	v_mov_b32_e32 v107, v2
	v_mov_b32_e32 v108, v2
	v_mov_b32_e32 v109, v2
	v_mov_b32_e32 v110, v2
	v_mov_b32_e32 v111, v2
	v_mov_b32_e32 v112, v2
	v_mov_b32_e32 v113, v2
	v_mov_b32_e32 v122, v2
	v_mov_b32_e32 v123, v2
	v_mov_b32_e32 v124, v2
	v_mov_b32_e32 v125, v2
	v_mov_b32_e32 v126, v2
	v_mov_b32_e32 v127, v2
	v_mov_b32_e32 v128, v2
	v_mov_b32_e32 v129, v2
	.p2align 6

; template <class Epi, class Sched, bool ALIGN_EPI = false, bool SP2 = false>
; __device__ __forceinline__ void gemm_phase(PG8_LAS unsigned char* lds, const Gemm g, const Sched& S, const Epi& E) {
;     ...
;             const char* a1 = cA + (size_t)(t + 1) * kstep;
;             const char* a2 = last ? nA : cA + (size_t)(t + 2) * kstep; const char* b2 = last ? nB : cB + (size_t)(t + 2) * kstep;
;             const char* a3 = a2 + kstep; const char* b3 = b2 + kstep;
;     ...
; #pragma unroll
;         for (int a = 0; a < 2; ++a)
; #pragma unroll
;             for (int b = 0; b < 2; ++b)
; #pragma unroll
;                 for (int m = 0; m < 4; ++m)
; #pragma unroll
;                     for (int n = 0; n < 2; ++n) acc[a][b][m][n] = (f32x4){0.f, 0.f, 0.f, 0.f};
.LBB0_1032:
	s_add_u32 s28, s28, 0x160080
	s_addc_u32 s29, s29, 0
	s_add_u32 s57, s30, 0x100
	v_mov_b32_e32 v2, 0
	s_addc_u32 s58, s31, 0
	s_mov_b32 s59, -2
	v_mov_b32_e32 v3, v2
	v_mov_b32_e32 v4, v2
	v_mov_b32_e32 v5, v2
	v_mov_b32_e32 v6, v2
	v_mov_b32_e32 v7, v2
	v_mov_b32_e32 v8, v2
	v_mov_b32_e32 v9, v2
	v_mov_b32_e32 v10, v2
	v_mov_b32_e32 v11, v2
	v_mov_b32_e32 v12, v2
	v_mov_b32_e32 v13, v2
	v_mov_b32_e32 v14, v2
	v_mov_b32_e32 v15, v2
	v_mov_b32_e32 v16, v2
	v_mov_b32_e32 v17, v2
	v_mov_b32_e32 v26, v2
	v_mov_b32_e32 v27, v2
	v_mov_b32_e32 v28, v2
	v_mov_b32_e32 v29, v2
	v_mov_b32_e32 v30, v2
	v_mov_b32_e32 v31, v2
	v_mov_b32_e32 v32, v2
	v_mov_b32_e32 v33, v2
	v_mov_b32_e32 v42, v2
	v_mov_b32_e32 v43, v2
	v_mov_b32_e32 v44, v2
	v_mov_b32_e32 v45, v2
	v_mov_b32_e32 v46, v2
	v_mov_b32_e32 v47, v2
	v_mov_b32_e32 v48, v2
	v_mov_b32_e32 v49, v2
	v_mov_b32_e32 v18, v2
	v_mov_b32_e32 v19, v2
	v_mov_b32_e32 v20, v2
	v_mov_b32_e32 v21, v2
	v_mov_b32_e32 v22, v2
	v_mov_b32_e32 v23, v2
	v_mov_b32_e32 v24, v2
	v_mov_b32_e32 v25, v2
	v_mov_b32_e32 v34, v2
	v_mov_b32_e32 v35, v2
	v_mov_b32_e32 v36, v2
	v_mov_b32_e32 v37, v2
	v_mov_b32_e32 v38, v2
	v_mov_b32_e32 v39, v2
	v_mov_b32_e32 v40, v2
	v_mov_b32_e32 v41, v2
	v_mov_b32_e32 v50, v2
	v_mov_b32_e32 v51, v2
	v_mov_b32_e32 v52, v2
	v_mov_b32_e32 v53, v2
	v_mov_b32_e32 v54, v2
	v_mov_b32_e32 v55, v2
	v_mov_b32_e32 v56, v2
	v_mov_b32_e32 v57, v2
	v_mov_b32_e32 v58, v2
	v_mov_b32_e32 v59, v2
	v_mov_b32_e32 v60, v2
	v_mov_b32_e32 v61, v2
	v_mov_b32_e32 v62, v2
	v_mov_b32_e32 v63, v2
	v_mov_b32_e32 v64, v2
	v_mov_b32_e32 v65, v2
	v_mov_b32_e32 v66, v2
	v_mov_b32_e32 v67, v2
	v_mov_b32_e32 v68, v2
	v_mov_b32_e32 v69, v2
	v_mov_b32_e32 v70, v2
	v_mov_b32_e32 v71, v2
	v_mov_b32_e32 v72, v2
	v_mov_b32_e32 v73, v2
	v_mov_b32_e32 v74, v2
	v_mov_b32_e32 v75, v2
	v_mov_b32_e32 v76, v2
	v_mov_b32_e32 v77, v2
	v_mov_b32_e32 v78, v2
	v_mov_b32_e32 v79, v2
	v_mov_b32_e32 v80, v2
	v_mov_b32_e32 v81, v2
	v_mov_b32_e32 v90, v2
	v_mov_b32_e32 v91, v2
	v_mov_b32_e32 v92, v2
	v_mov_b32_e32 v93, v2
	v_mov_b32_e32 v94, v2
	v_mov_b32_e32 v95, v2
	v_mov_b32_e32 v96, v2
	v_mov_b32_e32 v97, v2
	v_mov_b32_e32 v106, v2
	v_mov_b32_e32 v107, v2
	v_mov_b32_e32 v108, v2
	v_mov_b32_e32 v109, v2
	v_mov_b32_e32 v110, v2
	v_mov_b32_e32 v111, v2
	v_mov_b32_e32 v112, v2
	v_mov_b32_e32 v113, v2
	v_mov_b32_e32 v82, v2
	v_mov_b32_e32 v83, v2
	v_mov_b32_e32 v84, v2
	v_mov_b32_e32 v85, v2
	v_mov_b32_e32 v86, v2
	v_mov_b32_e32 v87, v2
	v_mov_b32_e32 v88, v2
	v_mov_b32_e32 v89, v2
	v_mov_b32_e32 v98, v2
	v_mov_b32_e32 v99, v2
	v_mov_b32_e32 v100, v2
	v_mov_b32_e32 v101, v2
	v_mov_b32_e32 v102, v2
	v_mov_b32_e32 v103, v2
	v_mov_b32_e32 v104, v2
	v_mov_b32_e32 v105, v2
	v_mov_b32_e32 v114, v2
	v_mov_b32_e32 v115, v2
	v_mov_b32_e32 v116, v2
	v_mov_b32_e32 v117, v2
	v_mov_b32_e32 v118, v2
	v_mov_b32_e32 v119, v2
	v_mov_b32_e32 v120, v2
	v_mov_b32_e32 v121, v2
	v_mov_b32_e32 v122, v2
	v_mov_b32_e32 v123, v2
	v_mov_b32_e32 v124, v2
	v_mov_b32_e32 v125, v2
	v_mov_b32_e32 v126, v2
	v_mov_b32_e32 v127, v2
	v_mov_b32_e32 v128, v2
	v_mov_b32_e32 v129, v2
	.p2align 6

; template <class Epi, class Sched, bool ALIGN_EPI = false, bool SP2 = false>
; __device__ __forceinline__ void gemm_phase(PG8_LAS unsigned char* lds, const Gemm g, const Sched& S, const Epi& E) {
;     ...
;         const bool has_next = S.next(ui + 1, nxt);
;         const char* nA = has_next ? (const char*)g.A + (size_t)nxt.pm * tstepA : cA; const char* nB = has_next ? (const char*)g.Bt + (size_t)nxt.pn * tstepB : cB;
;         for (int t = 0; t < nt; t += 2) {
;             const bool last = (t == nt - 2);
;             const char* a1 = cA + (size_t)(t + 1) * kstep;
;             const char* a2 = last ? nA : cA + (size_t)(t + 2) * kstep; const char* b2 = last ? nB : cB + (size_t)(t + 2) * kstep;
;             const char* a3 = a2 + kstep; const char* b3 = b2 + kstep;
;     ...
; #pragma unroll
;         for (int a = 0; a < 2; ++a)
; #pragma unroll
;             for (int b = 0; b < 2; ++b)
; #pragma unroll
;                 for (int m = 0; m < 4; ++m)
; #pragma unroll
;                     for (int n = 0; n < 2; ++n) acc[a][b][m][n] = (f32x4){0.f, 0.f, 0.f, 0.f};
.LBB0_1162:
	s_ashr_i32 s29, s28, 31
	s_lshl_b64 s[34:35], s[28:29], 18
	s_add_u32 s34, s22, s34
	s_addc_u32 s35, s23, s35
	s_and_b64 s[6:7], s[6:7], exec
	s_cselect_b32 s29, s35, s37
	s_cselect_b32 s57, s34, s36
	s_add_u32 s6, s38, 0x30080
	s_addc_u32 s7, s39, 0
	s_add_u32 s58, s36, 0x100
	v_mov_b32_e32 v2, 0
	s_addc_u32 s59, s37, 0
	s_mov_b32 s60, -2
	v_mov_b32_e32 v3, v2
	v_mov_b32_e32 v4, v2
	v_mov_b32_e32 v5, v2
	v_mov_b32_e32 v6, v2
	v_mov_b32_e32 v7, v2
	v_mov_b32_e32 v8, v2
	v_mov_b32_e32 v9, v2
	v_mov_b32_e32 v10, v2
	v_mov_b32_e32 v11, v2
	v_mov_b32_e32 v12, v2
	v_mov_b32_e32 v13, v2
	v_mov_b32_e32 v14, v2
	v_mov_b32_e32 v15, v2
	v_mov_b32_e32 v16, v2
	v_mov_b32_e32 v17, v2
	v_mov_b32_e32 v22, v2
	v_mov_b32_e32 v23, v2
	v_mov_b32_e32 v24, v2
	v_mov_b32_e32 v25, v2
	v_mov_b32_e32 v30, v2
	v_mov_b32_e32 v31, v2
	v_mov_b32_e32 v32, v2
	v_mov_b32_e32 v33, v2
	v_mov_b32_e32 v38, v2
	v_mov_b32_e32 v39, v2
	v_mov_b32_e32 v40, v2
	v_mov_b32_e32 v41, v2
	v_mov_b32_e32 v46, v2
	v_mov_b32_e32 v47, v2
	v_mov_b32_e32 v48, v2
	v_mov_b32_e32 v49, v2
	v_mov_b32_e32 v18, v2
	v_mov_b32_e32 v19, v2
	v_mov_b32_e32 v20, v2
	v_mov_b32_e32 v21, v2
	v_mov_b32_e32 v26, v2
	v_mov_b32_e32 v27, v2
	v_mov_b32_e32 v28, v2
	v_mov_b32_e32 v29, v2
	v_mov_b32_e32 v34, v2
	v_mov_b32_e32 v35, v2
	v_mov_b32_e32 v36, v2
	v_mov_b32_e32 v37, v2
	v_mov_b32_e32 v42, v2
	v_mov_b32_e32 v43, v2
	v_mov_b32_e32 v44, v2
	v_mov_b32_e32 v45, v2
	v_mov_b32_e32 v50, v2
	v_mov_b32_e32 v51, v2
	v_mov_b32_e32 v52, v2
	v_mov_b32_e32 v53, v2
	v_mov_b32_e32 v54, v2
	v_mov_b32_e32 v55, v2
	v_mov_b32_e32 v56, v2
	v_mov_b32_e32 v57, v2
	v_mov_b32_e32 v58, v2
	v_mov_b32_e32 v59, v2
	v_mov_b32_e32 v60, v2
	v_mov_b32_e32 v61, v2
	v_mov_b32_e32 v62, v2
	v_mov_b32_e32 v63, v2
	v_mov_b32_e32 v64, v2
	v_mov_b32_e32 v65, v2
	v_mov_b32_e32 v66, v2
	v_mov_b32_e32 v67, v2
	v_mov_b32_e32 v68, v2
	v_mov_b32_e32 v69, v2
	v_mov_b32_e32 v70, v2
	v_mov_b32_e32 v71, v2
	v_mov_b32_e32 v72, v2
	v_mov_b32_e32 v73, v2
	v_mov_b32_e32 v74, v2
	v_mov_b32_e32 v75, v2
	v_mov_b32_e32 v76, v2
	v_mov_b32_e32 v77, v2
	v_mov_b32_e32 v78, v2
	v_mov_b32_e32 v79, v2
	v_mov_b32_e32 v80, v2
	v_mov_b32_e32 v81, v2
	v_mov_b32_e32 v86, v2
	v_mov_b32_e32 v87, v2
	v_mov_b32_e32 v88, v2
	v_mov_b32_e32 v89, v2
	v_mov_b32_e32 v94, v2
	v_mov_b32_e32 v95, v2
	v_mov_b32_e32 v96, v2
	v_mov_b32_e32 v97, v2
	v_mov_b32_e32 v102, v2
	v_mov_b32_e32 v103, v2
	v_mov_b32_e32 v104, v2
	v_mov_b32_e32 v105, v2
	v_mov_b32_e32 v110, v2
	v_mov_b32_e32 v111, v2
	v_mov_b32_e32 v112, v2
	v_mov_b32_e32 v113, v2
	v_mov_b32_e32 v82, v2
	v_mov_b32_e32 v83, v2
	v_mov_b32_e32 v84, v2
	v_mov_b32_e32 v85, v2
	v_mov_b32_e32 v90, v2
	v_mov_b32_e32 v91, v2
	v_mov_b32_e32 v92, v2
	v_mov_b32_e32 v93, v2
	v_mov_b32_e32 v98, v2
	v_mov_b32_e32 v99, v2
	v_mov_b32_e32 v100, v2
	v_mov_b32_e32 v101, v2
	v_mov_b32_e32 v106, v2
	v_mov_b32_e32 v107, v2
	v_mov_b32_e32 v108, v2
	v_mov_b32_e32 v109, v2
	v_mov_b32_e32 v114, v2
	v_mov_b32_e32 v115, v2
	v_mov_b32_e32 v116, v2
	v_mov_b32_e32 v117, v2
	v_mov_b32_e32 v118, v2
	v_mov_b32_e32 v119, v2
	v_mov_b32_e32 v120, v2
	v_mov_b32_e32 v121, v2
	v_mov_b32_e32 v122, v2
	v_mov_b32_e32 v123, v2
	v_mov_b32_e32 v124, v2
	v_mov_b32_e32 v125, v2
	v_mov_b32_e32 v126, v2
	v_mov_b32_e32 v127, v2
	v_mov_b32_e32 v128, v2
	v_mov_b32_e32 v129, v2
	.p2align 6

; template <class Epi, class Sched, bool ALIGN_EPI = false, bool SP2 = false>
; __device__ __forceinline__ void gemm_phase(PG8_LAS unsigned char* lds, const Gemm g, const Sched& S, const Epi& E) {
;     ...
;             const char* a1 = cA + (size_t)(t + 1) * kstep;
;             const char* a2 = last ? nA : cA + (size_t)(t + 2) * kstep; const char* b2 = last ? nB : cB + (size_t)(t + 2) * kstep;
;             const char* a3 = a2 + kstep; const char* b3 = b2 + kstep;
;     ...
; #pragma unroll
;         for (int a = 0; a < 2; ++a)
; #pragma unroll
;             for (int b = 0; b < 2; ++b)
; #pragma unroll
;                 for (int m = 0; m < 4; ++m)
; #pragma unroll
;                     for (int n = 0; n < 2; ++n) acc[a][b][m][n] = (f32x4){0.f, 0.f, 0.f, 0.f};
.LBB0_1289:
	s_add_u32 s0, s0, 0x30080
	s_addc_u32 s1, s1, 0
	s_add_u32 s40, s2, 0x100
	v_mov_b32_e32 v2, 0
	s_addc_u32 s41, s3, 0
	s_mov_b32 s42, -2
	v_mov_b32_e32 v3, v2
	v_mov_b32_e32 v4, v2
	v_mov_b32_e32 v5, v2
	v_mov_b32_e32 v6, v2
	v_mov_b32_e32 v7, v2
	v_mov_b32_e32 v8, v2
	v_mov_b32_e32 v9, v2
	v_mov_b32_e32 v18, v2
	v_mov_b32_e32 v19, v2
	v_mov_b32_e32 v20, v2
	v_mov_b32_e32 v21, v2
	v_mov_b32_e32 v22, v2
	v_mov_b32_e32 v23, v2
	v_mov_b32_e32 v24, v2
	v_mov_b32_e32 v25, v2
	v_mov_b32_e32 v34, v2
	v_mov_b32_e32 v35, v2
	v_mov_b32_e32 v36, v2
	v_mov_b32_e32 v37, v2
	v_mov_b32_e32 v38, v2
	v_mov_b32_e32 v39, v2
	v_mov_b32_e32 v40, v2
	v_mov_b32_e32 v41, v2
	v_mov_b32_e32 v50, v2
	v_mov_b32_e32 v51, v2
	v_mov_b32_e32 v52, v2
	v_mov_b32_e32 v53, v2
	v_mov_b32_e32 v54, v2
	v_mov_b32_e32 v55, v2
	v_mov_b32_e32 v56, v2
	v_mov_b32_e32 v57, v2
	v_mov_b32_e32 v10, v2
	v_mov_b32_e32 v11, v2
	v_mov_b32_e32 v12, v2
	v_mov_b32_e32 v13, v2
	v_mov_b32_e32 v14, v2
	v_mov_b32_e32 v15, v2
	v_mov_b32_e32 v16, v2
	v_mov_b32_e32 v17, v2
	v_mov_b32_e32 v26, v2
	v_mov_b32_e32 v27, v2
	v_mov_b32_e32 v28, v2
	v_mov_b32_e32 v29, v2
	v_mov_b32_e32 v30, v2
	v_mov_b32_e32 v31, v2
	v_mov_b32_e32 v32, v2
	v_mov_b32_e32 v33, v2
	v_mov_b32_e32 v42, v2
	v_mov_b32_e32 v43, v2
	v_mov_b32_e32 v44, v2
	v_mov_b32_e32 v45, v2
	v_mov_b32_e32 v46, v2
	v_mov_b32_e32 v47, v2
	v_mov_b32_e32 v48, v2
	v_mov_b32_e32 v49, v2
	v_mov_b32_e32 v58, v2
	v_mov_b32_e32 v59, v2
	v_mov_b32_e32 v60, v2
	v_mov_b32_e32 v61, v2
	v_mov_b32_e32 v62, v2
	v_mov_b32_e32 v63, v2
	v_mov_b32_e32 v64, v2
	v_mov_b32_e32 v65, v2
	v_mov_b32_e32 v66, v2
	v_mov_b32_e32 v67, v2
	v_mov_b32_e32 v68, v2
	v_mov_b32_e32 v69, v2
	v_mov_b32_e32 v70, v2
	v_mov_b32_e32 v71, v2
	v_mov_b32_e32 v72, v2
	v_mov_b32_e32 v73, v2
	v_mov_b32_e32 v82, v2
	v_mov_b32_e32 v83, v2
	v_mov_b32_e32 v84, v2
	v_mov_b32_e32 v85, v2
	v_mov_b32_e32 v86, v2
	v_mov_b32_e32 v87, v2
	v_mov_b32_e32 v88, v2
	v_mov_b32_e32 v89, v2
	v_mov_b32_e32 v98, v2
	v_mov_b32_e32 v99, v2
	v_mov_b32_e32 v100, v2
	v_mov_b32_e32 v101, v2
	v_mov_b32_e32 v102, v2
	v_mov_b32_e32 v103, v2
	v_mov_b32_e32 v104, v2
	v_mov_b32_e32 v105, v2
	v_mov_b32_e32 v114, v2
	v_mov_b32_e32 v115, v2
	v_mov_b32_e32 v116, v2
	v_mov_b32_e32 v117, v2
	v_mov_b32_e32 v118, v2
	v_mov_b32_e32 v119, v2
	v_mov_b32_e32 v120, v2
	v_mov_b32_e32 v121, v2
	v_mov_b32_e32 v74, v2
	v_mov_b32_e32 v75, v2
	v_mov_b32_e32 v76, v2
	v_mov_b32_e32 v77, v2
	v_mov_b32_e32 v78, v2
	v_mov_b32_e32 v79, v2
	v_mov_b32_e32 v80, v2
	v_mov_b32_e32 v81, v2
	v_mov_b32_e32 v90, v2
	v_mov_b32_e32 v91, v2
	v_mov_b32_e32 v92, v2
	v_mov_b32_e32 v93, v2
	v_mov_b32_e32 v94, v2
	v_mov_b32_e32 v95, v2
	v_mov_b32_e32 v96, v2
	v_mov_b32_e32 v97, v2
	v_mov_b32_e32 v106, v2
	v_mov_b32_e32 v107, v2
	v_mov_b32_e32 v108, v2
	v_mov_b32_e32 v109, v2
	v_mov_b32_e32 v110, v2
	v_mov_b32_e32 v111, v2
	v_mov_b32_e32 v112, v2
	v_mov_b32_e32 v113, v2
	v_mov_b32_e32 v122, v2
	v_mov_b32_e32 v123, v2
	v_mov_b32_e32 v124, v2
	v_mov_b32_e32 v125, v2
	v_mov_b32_e32 v126, v2
	v_mov_b32_e32 v127, v2
	v_mov_b32_e32 v128, v2
	v_mov_b32_e32 v129, v2
	.p2align 6

; template <class Epi, class Sched, bool ALIGN_EPI = false, bool SP2 = false>
; __device__ __forceinline__ void gemm_phase(PG8_LAS unsigned char* lds, const Gemm g, const Sched& S, const Epi& E) {
;     ...
;         const bool has_next = S.next(ui + 1, nxt);
;         const char* nA = has_next ? (const char*)g.A + (size_t)nxt.pm * tstepA : cA; const char* nB = has_next ? (const char*)g.Bt + (size_t)nxt.pn * tstepB : cB;
;         for (int t = 0; t < nt; t += 2) {
;             const bool last = (t == nt - 2);
;             const char* a1 = cA + (size_t)(t + 1) * kstep;
;             const char* a2 = last ? nA : cA + (size_t)(t + 2) * kstep; const char* b2 = last ? nB : cB + (size_t)(t + 2) * kstep;
;             const char* a3 = a2 + kstep; const char* b3 = b2 + kstep;
;     ...
; #pragma unroll
;         for (int a = 0; a < 2; ++a)
; #pragma unroll
;             for (int b = 0; b < 2; ++b)
; #pragma unroll
;                 for (int m = 0; m < 4; ++m)
; #pragma unroll
;                     for (int n = 0; n < 2; ++n) acc[a][b][m][n] = (f32x4){0.f, 0.f, 0.f, 0.f};
.LBB0_1356:
	s_ashr_i32 s29, s28, 31
	s_lshl_b64 s[30:31], s[28:29], 20
	s_add_u32 s30, s86, s30
	s_addc_u32 s31, s87, s31
	s_and_b64 s[34:35], s[4:5], exec
	s_cselect_b32 s29, s31, s3
	s_cselect_b32 s53, s30, s2
	s_ashr_i32 s27, s26, 31
	s_lshl_b64 s[34:35], s[26:27], 20
	s_add_u32 s34, s88, s34
	s_addc_u32 s35, s89, s35
	s_and_b64 s[38:39], s[4:5], exec
	s_cselect_b32 s27, s35, s37
	s_cselect_b32 s54, s34, s36
	s_add_u32 s2, s2, 0x80080
	s_addc_u32 s3, s3, 0
	s_add_u32 s55, s36, 0x100
	v_mov_b32_e32 v2, 0
	s_addc_u32 s56, s37, 0
	s_mov_b32 s57, -2
	v_mov_b32_e32 v3, v2
	v_mov_b32_e32 v4, v2
	v_mov_b32_e32 v5, v2
	v_mov_b32_e32 v6, v2
	v_mov_b32_e32 v7, v2
	v_mov_b32_e32 v8, v2
	v_mov_b32_e32 v9, v2
	v_mov_b32_e32 v18, v2
	v_mov_b32_e32 v19, v2
	v_mov_b32_e32 v20, v2
	v_mov_b32_e32 v21, v2
	v_mov_b32_e32 v22, v2
	v_mov_b32_e32 v23, v2
	v_mov_b32_e32 v24, v2
	v_mov_b32_e32 v25, v2
	v_mov_b32_e32 v34, v2
	v_mov_b32_e32 v35, v2
	v_mov_b32_e32 v36, v2
	v_mov_b32_e32 v37, v2
	v_mov_b32_e32 v38, v2
	v_mov_b32_e32 v39, v2
	v_mov_b32_e32 v40, v2
	v_mov_b32_e32 v41, v2
	v_mov_b32_e32 v50, v2
	v_mov_b32_e32 v51, v2
	v_mov_b32_e32 v52, v2
	v_mov_b32_e32 v53, v2
	v_mov_b32_e32 v54, v2
	v_mov_b32_e32 v55, v2
	v_mov_b32_e32 v56, v2
	v_mov_b32_e32 v57, v2
	v_mov_b32_e32 v10, v2
	v_mov_b32_e32 v11, v2
	v_mov_b32_e32 v12, v2
	v_mov_b32_e32 v13, v2
	v_mov_b32_e32 v14, v2
	v_mov_b32_e32 v15, v2
	v_mov_b32_e32 v16, v2
	v_mov_b32_e32 v17, v2
	v_mov_b32_e32 v26, v2
	v_mov_b32_e32 v27, v2
	v_mov_b32_e32 v28, v2
	v_mov_b32_e32 v29, v2
	v_mov_b32_e32 v30, v2
	v_mov_b32_e32 v31, v2
	v_mov_b32_e32 v32, v2
	v_mov_b32_e32 v33, v2
	v_mov_b32_e32 v42, v2
	v_mov_b32_e32 v43, v2
	v_mov_b32_e32 v44, v2
	v_mov_b32_e32 v45, v2
	v_mov_b32_e32 v46, v2
	v_mov_b32_e32 v47, v2
	v_mov_b32_e32 v48, v2
	v_mov_b32_e32 v49, v2
	v_mov_b32_e32 v58, v2
	v_mov_b32_e32 v59, v2
	v_mov_b32_e32 v60, v2
	v_mov_b32_e32 v61, v2
	v_mov_b32_e32 v62, v2
	v_mov_b32_e32 v63, v2
	v_mov_b32_e32 v64, v2
	v_mov_b32_e32 v65, v2
	v_mov_b32_e32 v82, v2
	v_mov_b32_e32 v83, v2
	v_mov_b32_e32 v84, v2
	v_mov_b32_e32 v85, v2
	v_mov_b32_e32 v86, v2
	v_mov_b32_e32 v87, v2
	v_mov_b32_e32 v88, v2
	v_mov_b32_e32 v89, v2
	v_mov_b32_e32 v98, v2
	v_mov_b32_e32 v99, v2
	v_mov_b32_e32 v100, v2
	v_mov_b32_e32 v101, v2
	v_mov_b32_e32 v102, v2
	v_mov_b32_e32 v103, v2
	v_mov_b32_e32 v104, v2
	v_mov_b32_e32 v105, v2
	v_mov_b32_e32 v114, v2
	v_mov_b32_e32 v115, v2
	v_mov_b32_e32 v116, v2
	v_mov_b32_e32 v117, v2
	v_mov_b32_e32 v118, v2
	v_mov_b32_e32 v119, v2
	v_mov_b32_e32 v120, v2
	v_mov_b32_e32 v121, v2
	v_mov_b32_e32 v130, v2
	v_mov_b32_e32 v131, v2
	v_mov_b32_e32 v132, v2
	v_mov_b32_e32 v133, v2
	v_mov_b32_e32 v134, v2
	v_mov_b32_e32 v135, v2
	v_mov_b32_e32 v136, v2
	v_mov_b32_e32 v137, v2
	v_mov_b32_e32 v90, v2
	v_mov_b32_e32 v91, v2
	v_mov_b32_e32 v92, v2
	v_mov_b32_e32 v93, v2
	v_mov_b32_e32 v94, v2
	v_mov_b32_e32 v95, v2
	v_mov_b32_e32 v96, v2
	v_mov_b32_e32 v97, v2
	v_mov_b32_e32 v106, v2
	v_mov_b32_e32 v107, v2
	v_mov_b32_e32 v108, v2
	v_mov_b32_e32 v109, v2
	v_mov_b32_e32 v110, v2
	v_mov_b32_e32 v111, v2
	v_mov_b32_e32 v112, v2
	v_mov_b32_e32 v113, v2
	v_mov_b32_e32 v122, v2
	v_mov_b32_e32 v123, v2
	v_mov_b32_e32 v124, v2
	v_mov_b32_e32 v125, v2
	v_mov_b32_e32 v126, v2
	v_mov_b32_e32 v127, v2
	v_mov_b32_e32 v128, v2
	v_mov_b32_e32 v129, v2
	v_mov_b32_e32 v138, v2
	v_mov_b32_e32 v139, v2
	v_mov_b32_e32 v140, v2
	v_mov_b32_e32 v141, v2
	v_mov_b32_e32 v142, v2
	v_mov_b32_e32 v143, v2
	v_mov_b32_e32 v144, v2
	v_mov_b32_e32 v145, v2
	.p2align 6

; template <class Epi, class Sched, bool ALIGN_EPI = false, bool SP2 = false>
; __device__ __forceinline__ void gemm_phase(PG8_LAS unsigned char* lds, const Gemm g, const Sched& S, const Epi& E) {
;     ...
;         const bool has_next = S.next(ui + 1, nxt);
;         const char* nA = has_next ? (const char*)g.A + (size_t)nxt.pm * tstepA : cA; const char* nB = has_next ? (const char*)g.Bt + (size_t)nxt.pn * tstepB : cB;
;         for (int t = 0; t < nt; t += 2) {
;             const bool last = (t == nt - 2);
;             const char* a1 = cA + (size_t)(t + 1) * kstep;
;             const char* a2 = last ? nA : cA + (size_t)(t + 2) * kstep; const char* b2 = last ? nB : cB + (size_t)(t + 2) * kstep;
;             const char* a3 = a2 + kstep; const char* b3 = b2 + kstep;
;     ...
; #pragma unroll
;         for (int a = 0; a < 2; ++a)
; #pragma unroll
;             for (int b = 0; b < 2; ++b)
; #pragma unroll
;                 for (int m = 0; m < 4; ++m)
; #pragma unroll
;                     for (int n = 0; n < 2; ++n) acc[a][b][m][n] = (f32x4){0.f, 0.f, 0.f, 0.f};
.LBB0_1486:
	s_ashr_i32 s13, s12, 31
	s_lshl_b64 s[14:15], s[12:13], 20
	s_add_u32 s14, s86, s14
	s_addc_u32 s15, s87, s15
	s_and_b64 s[16:17], s[4:5], exec
	s_cselect_b32 s13, s15, s23
	s_cselect_b32 s46, s14, s22
	s_ashr_i32 s11, s10, 31
	s_lshl_b64 s[16:17], s[10:11], 20
	s_add_u32 s16, s29, s16
	s_addc_u32 s17, s30, s17
	s_and_b64 s[26:27], s[4:5], exec
	s_cselect_b32 s11, s17, s25
	s_cselect_b32 s47, s16, s24
	s_add_u32 s22, s22, 0x80080
	s_addc_u32 s23, s23, 0
	s_add_u32 s48, s24, 0x100
	v_mov_b32_e32 v2, 0
	s_addc_u32 s49, s25, 0
	s_mov_b32 s50, -2
	v_mov_b32_e32 v3, v2
	v_mov_b32_e32 v4, v2
	v_mov_b32_e32 v5, v2
	v_mov_b32_e32 v6, v2
	v_mov_b32_e32 v7, v2
	v_mov_b32_e32 v8, v2
	v_mov_b32_e32 v9, v2
	v_mov_b32_e32 v18, v2
	v_mov_b32_e32 v19, v2
	v_mov_b32_e32 v20, v2
	v_mov_b32_e32 v21, v2
	v_mov_b32_e32 v22, v2
	v_mov_b32_e32 v23, v2
	v_mov_b32_e32 v24, v2
	v_mov_b32_e32 v25, v2
	v_mov_b32_e32 v34, v2
	v_mov_b32_e32 v35, v2
	v_mov_b32_e32 v36, v2
	v_mov_b32_e32 v37, v2
	v_mov_b32_e32 v38, v2
	v_mov_b32_e32 v39, v2
	v_mov_b32_e32 v40, v2
	v_mov_b32_e32 v41, v2
	v_mov_b32_e32 v50, v2
	v_mov_b32_e32 v51, v2
	v_mov_b32_e32 v52, v2
	v_mov_b32_e32 v53, v2
	v_mov_b32_e32 v54, v2
	v_mov_b32_e32 v55, v2
	v_mov_b32_e32 v56, v2
	v_mov_b32_e32 v57, v2
	v_mov_b32_e32 v10, v2
	v_mov_b32_e32 v11, v2
	v_mov_b32_e32 v12, v2
	v_mov_b32_e32 v13, v2
	v_mov_b32_e32 v14, v2
	v_mov_b32_e32 v15, v2
	v_mov_b32_e32 v16, v2
	v_mov_b32_e32 v17, v2
	v_mov_b32_e32 v26, v2
	v_mov_b32_e32 v27, v2
	v_mov_b32_e32 v28, v2
	v_mov_b32_e32 v29, v2
	v_mov_b32_e32 v30, v2
	v_mov_b32_e32 v31, v2
	v_mov_b32_e32 v32, v2
	v_mov_b32_e32 v33, v2
	v_mov_b32_e32 v42, v2
	v_mov_b32_e32 v43, v2
	v_mov_b32_e32 v44, v2
	v_mov_b32_e32 v45, v2
	v_mov_b32_e32 v46, v2
	v_mov_b32_e32 v47, v2
	v_mov_b32_e32 v48, v2
	v_mov_b32_e32 v49, v2
	v_mov_b32_e32 v58, v2
	v_mov_b32_e32 v59, v2
	v_mov_b32_e32 v60, v2
	v_mov_b32_e32 v61, v2
	v_mov_b32_e32 v62, v2
	v_mov_b32_e32 v63, v2
	v_mov_b32_e32 v64, v2
	v_mov_b32_e32 v65, v2
	v_mov_b32_e32 v66, v2
	v_mov_b32_e32 v67, v2
	v_mov_b32_e32 v68, v2
	v_mov_b32_e32 v69, v2
	v_mov_b32_e32 v70, v2
	v_mov_b32_e32 v71, v2
	v_mov_b32_e32 v72, v2
	v_mov_b32_e32 v73, v2
	v_mov_b32_e32 v82, v2
	v_mov_b32_e32 v83, v2
	v_mov_b32_e32 v84, v2
	v_mov_b32_e32 v85, v2
	v_mov_b32_e32 v86, v2
	v_mov_b32_e32 v87, v2
	v_mov_b32_e32 v88, v2
	v_mov_b32_e32 v89, v2
	v_mov_b32_e32 v98, v2
	v_mov_b32_e32 v99, v2
	v_mov_b32_e32 v100, v2
	v_mov_b32_e32 v101, v2
	v_mov_b32_e32 v102, v2
	v_mov_b32_e32 v103, v2
	v_mov_b32_e32 v104, v2
	v_mov_b32_e32 v105, v2
	v_mov_b32_e32 v114, v2
	v_mov_b32_e32 v115, v2
	v_mov_b32_e32 v116, v2
	v_mov_b32_e32 v117, v2
	v_mov_b32_e32 v118, v2
	v_mov_b32_e32 v119, v2
	v_mov_b32_e32 v120, v2
	v_mov_b32_e32 v121, v2
	v_mov_b32_e32 v74, v2
	v_mov_b32_e32 v75, v2
	v_mov_b32_e32 v76, v2
	v_mov_b32_e32 v77, v2
	v_mov_b32_e32 v78, v2
	v_mov_b32_e32 v79, v2
	v_mov_b32_e32 v80, v2
	v_mov_b32_e32 v81, v2
	v_mov_b32_e32 v90, v2
	v_mov_b32_e32 v91, v2
	v_mov_b32_e32 v92, v2
	v_mov_b32_e32 v93, v2
	v_mov_b32_e32 v94, v2
	v_mov_b32_e32 v95, v2
	v_mov_b32_e32 v96, v2
	v_mov_b32_e32 v97, v2
	v_mov_b32_e32 v106, v2
	v_mov_b32_e32 v107, v2
	v_mov_b32_e32 v108, v2
	v_mov_b32_e32 v109, v2
	v_mov_b32_e32 v110, v2
	v_mov_b32_e32 v111, v2
	v_mov_b32_e32 v112, v2
	v_mov_b32_e32 v113, v2
	v_mov_b32_e32 v122, v2
	v_mov_b32_e32 v123, v2
	v_mov_b32_e32 v124, v2
	v_mov_b32_e32 v125, v2
	v_mov_b32_e32 v126, v2
	v_mov_b32_e32 v127, v2
	v_mov_b32_e32 v128, v2
	v_mov_b32_e32 v129, v2
	.p2align 6

; template <class Epi, class Sched, bool ALIGN_EPI = false, bool SP2 = false>
; __device__ __forceinline__ void gemm_phase(PG8_LAS unsigned char* lds, const Gemm g, const Sched& S, const Epi& E) {
;     ...
;             const char* a1 = cA + (size_t)(t + 1) * kstep;
;             const char* a2 = last ? nA : cA + (size_t)(t + 2) * kstep; const char* b2 = last ? nB : cB + (size_t)(t + 2) * kstep;
;             const char* a3 = a2 + kstep; const char* b3 = b2 + kstep;
;     ...
; #pragma unroll
;         for (int a = 0; a < 2; ++a)
; #pragma unroll
;             for (int b = 0; b < 2; ++b)
; #pragma unroll
;                 for (int m = 0; m < 4; ++m)
; #pragma unroll
;                     for (int n = 0; n < 2; ++n) acc[a][b][m][n] = (f32x4){0.f, 0.f, 0.f, 0.f};
.LBB0_1707:
	s_add_u32 s24, s24, 0x160080
	s_addc_u32 s25, s25, 0
	s_add_u32 s55, s26, 0x100
	v_mov_b32_e32 v2, 0
	s_addc_u32 s56, s27, 0
	s_mov_b32 s57, -2
	v_mov_b32_e32 v3, v2
	v_mov_b32_e32 v4, v2
	v_mov_b32_e32 v5, v2
	v_mov_b32_e32 v6, v2
	v_mov_b32_e32 v7, v2
	v_mov_b32_e32 v8, v2
	v_mov_b32_e32 v9, v2
	v_mov_b32_e32 v10, v2
	v_mov_b32_e32 v11, v2
	v_mov_b32_e32 v12, v2
	v_mov_b32_e32 v13, v2
	v_mov_b32_e32 v14, v2
	v_mov_b32_e32 v15, v2
	v_mov_b32_e32 v16, v2
	v_mov_b32_e32 v17, v2
	v_mov_b32_e32 v26, v2
	v_mov_b32_e32 v27, v2
	v_mov_b32_e32 v28, v2
	v_mov_b32_e32 v29, v2
	v_mov_b32_e32 v30, v2
	v_mov_b32_e32 v31, v2
	v_mov_b32_e32 v32, v2
	v_mov_b32_e32 v33, v2
	v_mov_b32_e32 v42, v2
	v_mov_b32_e32 v43, v2
	v_mov_b32_e32 v44, v2
	v_mov_b32_e32 v45, v2
	v_mov_b32_e32 v46, v2
	v_mov_b32_e32 v47, v2
	v_mov_b32_e32 v48, v2
	v_mov_b32_e32 v49, v2
	v_mov_b32_e32 v18, v2
	v_mov_b32_e32 v19, v2
	v_mov_b32_e32 v20, v2
	v_mov_b32_e32 v21, v2
	v_mov_b32_e32 v22, v2
	v_mov_b32_e32 v23, v2
	v_mov_b32_e32 v24, v2
	v_mov_b32_e32 v25, v2
	v_mov_b32_e32 v34, v2
	v_mov_b32_e32 v35, v2
	v_mov_b32_e32 v36, v2
	v_mov_b32_e32 v37, v2
	v_mov_b32_e32 v38, v2
	v_mov_b32_e32 v39, v2
	v_mov_b32_e32 v40, v2
	v_mov_b32_e32 v41, v2
	v_mov_b32_e32 v50, v2
	v_mov_b32_e32 v51, v2
	v_mov_b32_e32 v52, v2
	v_mov_b32_e32 v53, v2
	v_mov_b32_e32 v54, v2
	v_mov_b32_e32 v55, v2
	v_mov_b32_e32 v56, v2
	v_mov_b32_e32 v57, v2
	v_mov_b32_e32 v58, v2
	v_mov_b32_e32 v59, v2
	v_mov_b32_e32 v60, v2
	v_mov_b32_e32 v61, v2
	v_mov_b32_e32 v62, v2
	v_mov_b32_e32 v63, v2
	v_mov_b32_e32 v64, v2
	v_mov_b32_e32 v65, v2
	v_mov_b32_e32 v66, v2
	v_mov_b32_e32 v67, v2
	v_mov_b32_e32 v68, v2
	v_mov_b32_e32 v69, v2
	v_mov_b32_e32 v70, v2
	v_mov_b32_e32 v71, v2
	v_mov_b32_e32 v72, v2
	v_mov_b32_e32 v73, v2
	v_mov_b32_e32 v74, v2
	v_mov_b32_e32 v75, v2
	v_mov_b32_e32 v76, v2
	v_mov_b32_e32 v77, v2
	v_mov_b32_e32 v78, v2
	v_mov_b32_e32 v79, v2
	v_mov_b32_e32 v80, v2
	v_mov_b32_e32 v81, v2
	v_mov_b32_e32 v90, v2
	v_mov_b32_e32 v91, v2
	v_mov_b32_e32 v92, v2
	v_mov_b32_e32 v93, v2
	v_mov_b32_e32 v94, v2
	v_mov_b32_e32 v95, v2
	v_mov_b32_e32 v96, v2
	v_mov_b32_e32 v97, v2
	v_mov_b32_e32 v106, v2
	v_mov_b32_e32 v107, v2
	v_mov_b32_e32 v108, v2
	v_mov_b32_e32 v109, v2
	v_mov_b32_e32 v110, v2
	v_mov_b32_e32 v111, v2
	v_mov_b32_e32 v112, v2
	v_mov_b32_e32 v113, v2
	v_mov_b32_e32 v82, v2
	v_mov_b32_e32 v83, v2
	v_mov_b32_e32 v84, v2
	v_mov_b32_e32 v85, v2
	v_mov_b32_e32 v86, v2
	v_mov_b32_e32 v87, v2
	v_mov_b32_e32 v88, v2
	v_mov_b32_e32 v89, v2
	v_mov_b32_e32 v98, v2
	v_mov_b32_e32 v99, v2
	v_mov_b32_e32 v100, v2
	v_mov_b32_e32 v101, v2
	v_mov_b32_e32 v102, v2
	v_mov_b32_e32 v103, v2
	v_mov_b32_e32 v104, v2
	v_mov_b32_e32 v105, v2
	v_mov_b32_e32 v114, v2
	v_mov_b32_e32 v115, v2
	v_mov_b32_e32 v116, v2
	v_mov_b32_e32 v117, v2
	v_mov_b32_e32 v118, v2
	v_mov_b32_e32 v119, v2
	v_mov_b32_e32 v120, v2
	v_mov_b32_e32 v121, v2
	v_mov_b32_e32 v122, v2
	v_mov_b32_e32 v123, v2
	v_mov_b32_e32 v124, v2
	v_mov_b32_e32 v125, v2
	v_mov_b32_e32 v126, v2
	v_mov_b32_e32 v127, v2
	v_mov_b32_e32 v128, v2
	v_mov_b32_e32 v129, v2
	.p2align 6

; template <class Epi, class Sched, bool ALIGN_EPI = false, bool SP2 = false>
; __device__ __forceinline__ void gemm_phase(PG8_LAS unsigned char* lds, const Gemm g, const Sched& S, const Epi& E) {
;     ...
;         const bool has_next = S.next(ui + 1, nxt);
;         const char* nA = has_next ? (const char*)g.A + (size_t)nxt.pm * tstepA : cA; const char* nB = has_next ? (const char*)g.Bt + (size_t)nxt.pn * tstepB : cB;
;         for (int t = 0; t < nt; t += 2) {
;             const bool last = (t == nt - 2);
;             const char* a1 = cA + (size_t)(t + 1) * kstep;
;             const char* a2 = last ? nA : cA + (size_t)(t + 2) * kstep; const char* b2 = last ? nB : cB + (size_t)(t + 2) * kstep;
;             const char* a3 = a2 + kstep; const char* b3 = b2 + kstep;
;     ...
; #pragma unroll
;         for (int a = 0; a < 2; ++a)
; #pragma unroll
;             for (int b = 0; b < 2; ++b)
; #pragma unroll
;                 for (int m = 0; m < 4; ++m)
; #pragma unroll
;                     for (int n = 0; n < 2; ++n) acc[a][b][m][n] = (f32x4){0.f, 0.f, 0.f, 0.f};
.LBB0_1838:
	s_ashr_i32 s25, s24, 31
	s_lshl_b64 s[26:27], s[24:25], 20
	s_add_u32 s26, s86, s26
	s_addc_u32 s27, s87, s27
	s_and_b64 s[28:29], s[8:9], exec
	s_cselect_b32 s11, s27, s13
	s_cselect_b32 s25, s26, s12
	s_ashr_i32 s23, s22, 31
	s_lshl_b64 s[28:29], s[22:23], 20
	v_readlane_b32 s34, v254, 2
	v_readlane_b32 s35, v254, 3
	s_add_u32 s28, s34, s28
	s_addc_u32 s29, s35, s29
	s_and_b64 s[34:35], s[8:9], exec
	s_cselect_b32 s23, s29, s31
	s_cselect_b32 s36, s28, s30
	s_add_u32 s12, s12, 0x80080
	s_addc_u32 s13, s13, 0
	s_add_u32 s37, s30, 0x100
	v_mov_b32_e32 v2, 0
	s_addc_u32 s38, s31, 0
	s_mov_b32 s39, -2
	v_mov_b32_e32 v3, v2
	v_mov_b32_e32 v4, v2
	v_mov_b32_e32 v5, v2
	v_mov_b32_e32 v6, v2
	v_mov_b32_e32 v7, v2
	v_mov_b32_e32 v8, v2
	v_mov_b32_e32 v9, v2
	v_mov_b32_e32 v18, v2
	v_mov_b32_e32 v19, v2
	v_mov_b32_e32 v20, v2
	v_mov_b32_e32 v21, v2
	v_mov_b32_e32 v22, v2
	v_mov_b32_e32 v23, v2
	v_mov_b32_e32 v24, v2
	v_mov_b32_e32 v25, v2
	v_mov_b32_e32 v34, v2
	v_mov_b32_e32 v35, v2
	v_mov_b32_e32 v36, v2
	v_mov_b32_e32 v37, v2
	v_mov_b32_e32 v38, v2
	v_mov_b32_e32 v39, v2
	v_mov_b32_e32 v40, v2
	v_mov_b32_e32 v41, v2
	v_mov_b32_e32 v50, v2
	v_mov_b32_e32 v51, v2
	v_mov_b32_e32 v52, v2
	v_mov_b32_e32 v53, v2
	v_mov_b32_e32 v54, v2
	v_mov_b32_e32 v55, v2
	v_mov_b32_e32 v56, v2
	v_mov_b32_e32 v57, v2
	v_mov_b32_e32 v10, v2
	v_mov_b32_e32 v11, v2
	v_mov_b32_e32 v12, v2
	v_mov_b32_e32 v13, v2
	v_mov_b32_e32 v14, v2
	v_mov_b32_e32 v15, v2
	v_mov_b32_e32 v16, v2
	v_mov_b32_e32 v17, v2
	v_mov_b32_e32 v26, v2
	v_mov_b32_e32 v27, v2
	v_mov_b32_e32 v28, v2
	v_mov_b32_e32 v29, v2
	v_mov_b32_e32 v30, v2
	v_mov_b32_e32 v31, v2
	v_mov_b32_e32 v32, v2
	v_mov_b32_e32 v33, v2
	v_mov_b32_e32 v42, v2
	v_mov_b32_e32 v43, v2
	v_mov_b32_e32 v44, v2
	v_mov_b32_e32 v45, v2
	v_mov_b32_e32 v46, v2
	v_mov_b32_e32 v47, v2
	v_mov_b32_e32 v48, v2
	v_mov_b32_e32 v49, v2
	v_mov_b32_e32 v58, v2
	v_mov_b32_e32 v59, v2
	v_mov_b32_e32 v60, v2
	v_mov_b32_e32 v61, v2
	v_mov_b32_e32 v62, v2
	v_mov_b32_e32 v63, v2
	v_mov_b32_e32 v64, v2
	v_mov_b32_e32 v65, v2
	v_mov_b32_e32 v66, v2
	v_mov_b32_e32 v67, v2
	v_mov_b32_e32 v68, v2
	v_mov_b32_e32 v69, v2
	v_mov_b32_e32 v70, v2
	v_mov_b32_e32 v71, v2
	v_mov_b32_e32 v72, v2
	v_mov_b32_e32 v73, v2
	v_mov_b32_e32 v82, v2
	v_mov_b32_e32 v83, v2
	v_mov_b32_e32 v84, v2
	v_mov_b32_e32 v85, v2
	v_mov_b32_e32 v86, v2
	v_mov_b32_e32 v87, v2
	v_mov_b32_e32 v88, v2
	v_mov_b32_e32 v89, v2
	v_mov_b32_e32 v98, v2
	v_mov_b32_e32 v99, v2
	v_mov_b32_e32 v100, v2
	v_mov_b32_e32 v101, v2
	v_mov_b32_e32 v102, v2
	v_mov_b32_e32 v103, v2
	v_mov_b32_e32 v104, v2
	v_mov_b32_e32 v105, v2
	v_mov_b32_e32 v114, v2
	v_mov_b32_e32 v115, v2
	v_mov_b32_e32 v116, v2
	v_mov_b32_e32 v117, v2
	v_mov_b32_e32 v118, v2
	v_mov_b32_e32 v119, v2
	v_mov_b32_e32 v120, v2
	v_mov_b32_e32 v121, v2
	v_mov_b32_e32 v74, v2
	v_mov_b32_e32 v75, v2
	v_mov_b32_e32 v76, v2
	v_mov_b32_e32 v77, v2
	v_mov_b32_e32 v78, v2
	v_mov_b32_e32 v79, v2
	v_mov_b32_e32 v80, v2
	v_mov_b32_e32 v81, v2
	v_mov_b32_e32 v90, v2
	v_mov_b32_e32 v91, v2
	v_mov_b32_e32 v92, v2
	v_mov_b32_e32 v93, v2
	v_mov_b32_e32 v94, v2
	v_mov_b32_e32 v95, v2
	v_mov_b32_e32 v96, v2
	v_mov_b32_e32 v97, v2
	v_mov_b32_e32 v106, v2
	v_mov_b32_e32 v107, v2
	v_mov_b32_e32 v108, v2
	v_mov_b32_e32 v109, v2
	v_mov_b32_e32 v110, v2
	v_mov_b32_e32 v111, v2
	v_mov_b32_e32 v112, v2
	v_mov_b32_e32 v113, v2
	v_mov_b32_e32 v122, v2
	v_mov_b32_e32 v123, v2
	v_mov_b32_e32 v124, v2
	v_mov_b32_e32 v125, v2
	v_mov_b32_e32 v126, v2
	v_mov_b32_e32 v127, v2
	v_mov_b32_e32 v128, v2
	v_mov_b32_e32 v129, v2
	.p2align 6

; template <class Epi, class Sched, bool ALIGN_EPI = false, bool SP2 = false>
; __device__ __forceinline__ void gemm_phase(PG8_LAS unsigned char* lds, const Gemm g, const Sched& S, const Epi& E) {
;     ...
;         const bool has_next = S.next(ui + 1, nxt);
;         const char* nA = has_next ? (const char*)g.A + (size_t)nxt.pm * tstepA : cA; const char* nB = has_next ? (const char*)g.Bt + (size_t)nxt.pn * tstepB : cB;
;         for (int t = 0; t < nt; t += 2) {
;             const bool last = (t == nt - 2);
;             const char* a1 = cA + (size_t)(t + 1) * kstep;
;             const char* a2 = last ? nA : cA + (size_t)(t + 2) * kstep; const char* b2 = last ? nB : cB + (size_t)(t + 2) * kstep;
;             const char* a3 = a2 + kstep; const char* b3 = b2 + kstep;
;     ...
; #pragma unroll
;         for (int a = 0; a < 2; ++a)
; #pragma unroll
;             for (int b = 0; b < 2; ++b)
; #pragma unroll
;                 for (int m = 0; m < 4; ++m)
; #pragma unroll
;                     for (int n = 0; n < 2; ++n) acc[a][b][m][n] = (f32x4){0.f, 0.f, 0.f, 0.f};
.LBB0_2258:
	s_ashr_i32 s23, s22, 31
	s_lshl_b64 s[24:25], s[22:23], 21
	s_add_u32 s24, s86, s24
	s_addc_u32 s25, s87, s25
	s_and_b64 s[26:27], s[4:5], exec
	s_cselect_b32 s23, s25, s29
	s_cselect_b32 s53, s24, s28
	s_ashr_i32 s21, s20, 31
	s_lshl_b64 s[26:27], s[20:21], 21
	s_add_u32 s26, s88, s26
	s_addc_u32 s27, s89, s27
	s_and_b64 s[34:35], s[4:5], exec
	s_cselect_b32 s21, s27, s31
	s_cselect_b32 s54, s26, s30
	s_add_u32 s28, s28, 0x100080
	s_addc_u32 s29, s29, 0
	s_add_u32 s55, s30, 0x100
	v_mov_b32_e32 v2, 0
	s_addc_u32 s56, s31, 0
	s_mov_b32 s57, -2
	v_mov_b32_e32 v3, v2
	v_mov_b32_e32 v4, v2
	v_mov_b32_e32 v5, v2
	v_mov_b32_e32 v6, v2
	v_mov_b32_e32 v7, v2
	v_mov_b32_e32 v8, v2
	v_mov_b32_e32 v9, v2
	v_mov_b32_e32 v10, v2
	v_mov_b32_e32 v11, v2
	v_mov_b32_e32 v12, v2
	v_mov_b32_e32 v13, v2
	v_mov_b32_e32 v14, v2
	v_mov_b32_e32 v15, v2
	v_mov_b32_e32 v16, v2
	v_mov_b32_e32 v17, v2
	v_mov_b32_e32 v26, v2
	v_mov_b32_e32 v27, v2
	v_mov_b32_e32 v28, v2
	v_mov_b32_e32 v29, v2
	v_mov_b32_e32 v30, v2
	v_mov_b32_e32 v31, v2
	v_mov_b32_e32 v32, v2
	v_mov_b32_e32 v33, v2
	v_mov_b32_e32 v42, v2
	v_mov_b32_e32 v43, v2
	v_mov_b32_e32 v44, v2
	v_mov_b32_e32 v45, v2
	v_mov_b32_e32 v46, v2
	v_mov_b32_e32 v47, v2
	v_mov_b32_e32 v48, v2
	v_mov_b32_e32 v49, v2
	v_mov_b32_e32 v18, v2
	v_mov_b32_e32 v19, v2
	v_mov_b32_e32 v20, v2
	v_mov_b32_e32 v21, v2
	v_mov_b32_e32 v22, v2
	v_mov_b32_e32 v23, v2
	v_mov_b32_e32 v24, v2
	v_mov_b32_e32 v25, v2
	v_mov_b32_e32 v34, v2
	v_mov_b32_e32 v35, v2
	v_mov_b32_e32 v36, v2
	v_mov_b32_e32 v37, v2
	v_mov_b32_e32 v38, v2
	v_mov_b32_e32 v39, v2
	v_mov_b32_e32 v40, v2
	v_mov_b32_e32 v41, v2
	v_mov_b32_e32 v50, v2
	v_mov_b32_e32 v51, v2
	v_mov_b32_e32 v52, v2
	v_mov_b32_e32 v53, v2
	v_mov_b32_e32 v54, v2
	v_mov_b32_e32 v55, v2
	v_mov_b32_e32 v56, v2
	v_mov_b32_e32 v57, v2
	v_mov_b32_e32 v58, v2
	v_mov_b32_e32 v59, v2
	v_mov_b32_e32 v60, v2
	v_mov_b32_e32 v61, v2
	v_mov_b32_e32 v62, v2
	v_mov_b32_e32 v63, v2
	v_mov_b32_e32 v64, v2
	v_mov_b32_e32 v65, v2
	v_mov_b32_e32 v66, v2
	v_mov_b32_e32 v67, v2
	v_mov_b32_e32 v68, v2
	v_mov_b32_e32 v69, v2
	v_mov_b32_e32 v70, v2
	v_mov_b32_e32 v71, v2
	v_mov_b32_e32 v72, v2
	v_mov_b32_e32 v73, v2
	v_mov_b32_e32 v74, v2
	v_mov_b32_e32 v75, v2
	v_mov_b32_e32 v76, v2
	v_mov_b32_e32 v77, v2
	v_mov_b32_e32 v78, v2
	v_mov_b32_e32 v79, v2
	v_mov_b32_e32 v80, v2
	v_mov_b32_e32 v81, v2
	v_mov_b32_e32 v90, v2
	v_mov_b32_e32 v91, v2
	v_mov_b32_e32 v92, v2
	v_mov_b32_e32 v93, v2
	v_mov_b32_e32 v94, v2
	v_mov_b32_e32 v95, v2
	v_mov_b32_e32 v96, v2
	v_mov_b32_e32 v97, v2
	v_mov_b32_e32 v106, v2
	v_mov_b32_e32 v107, v2
	v_mov_b32_e32 v108, v2
	v_mov_b32_e32 v109, v2
	v_mov_b32_e32 v110, v2
	v_mov_b32_e32 v111, v2
	v_mov_b32_e32 v112, v2
	v_mov_b32_e32 v113, v2
	v_mov_b32_e32 v82, v2
	v_mov_b32_e32 v83, v2
	v_mov_b32_e32 v84, v2
	v_mov_b32_e32 v85, v2
	v_mov_b32_e32 v86, v2
	v_mov_b32_e32 v87, v2
	v_mov_b32_e32 v88, v2
	v_mov_b32_e32 v89, v2
	v_mov_b32_e32 v98, v2
	v_mov_b32_e32 v99, v2
	v_mov_b32_e32 v100, v2
	v_mov_b32_e32 v101, v2
	v_mov_b32_e32 v102, v2
	v_mov_b32_e32 v103, v2
	v_mov_b32_e32 v104, v2
	v_mov_b32_e32 v105, v2
	v_mov_b32_e32 v114, v2
	v_mov_b32_e32 v115, v2
	v_mov_b32_e32 v116, v2
	v_mov_b32_e32 v117, v2
	v_mov_b32_e32 v118, v2
	v_mov_b32_e32 v119, v2
	v_mov_b32_e32 v120, v2
	v_mov_b32_e32 v121, v2
	v_mov_b32_e32 v122, v2
	v_mov_b32_e32 v123, v2
	v_mov_b32_e32 v124, v2
	v_mov_b32_e32 v125, v2
	v_mov_b32_e32 v126, v2
	v_mov_b32_e32 v127, v2
	v_mov_b32_e32 v128, v2
	v_mov_b32_e32 v129, v2
	.p2align 6

; template <class Epi, class Sched, bool ALIGN_EPI = false, bool SP2 = false>
; __device__ __forceinline__ void gemm_phase(PG8_LAS unsigned char* lds, const Gemm g, const Sched& S, const Epi& E) {
;     ...
;         const bool has_next = S.next(ui + 1, nxt);
;         const char* nA = has_next ? (const char*)g.A + (size_t)nxt.pm * tstepA : cA; const char* nB = has_next ? (const char*)g.Bt + (size_t)nxt.pn * tstepB : cB;
;         for (int t = 0; t < nt; t += 2) {
;             const bool last = (t == nt - 2);
;             const char* a1 = cA + (size_t)(t + 1) * kstep;
;             const char* a2 = last ? nA : cA + (size_t)(t + 2) * kstep; const char* b2 = last ? nB : cB + (size_t)(t + 2) * kstep;
;             const char* a3 = a2 + kstep; const char* b3 = b2 + kstep;
;     ...
; #pragma unroll
;         for (int a = 0; a < 2; ++a)
; #pragma unroll
;             for (int b = 0; b < 2; ++b)
; #pragma unroll
;                 for (int m = 0; m < 4; ++m)
; #pragma unroll
;                     for (int n = 0; n < 2; ++n) acc[a][b][m][n] = (f32x4){0.f, 0.f, 0.f, 0.f};
.LBB0_2386:
	s_ashr_i32 s13, s12, 31
	s_lshl_b64 s[14:15], s[12:13], 20
	s_add_u32 s14, s86, s14
	s_addc_u32 s15, s87, s15
	s_and_b64 s[16:17], s[4:5], exec
	s_cselect_b32 s13, s15, s21
	s_cselect_b32 s42, s14, s20
	s_ashr_i32 s11, s10, 31
	s_lshl_b64 s[16:17], s[10:11], 20
	v_readlane_b32 s24, v254, 0
	v_readlane_b32 s25, v254, 1
	s_add_u32 s16, s24, s16
	s_addc_u32 s17, s25, s17
	s_and_b64 s[24:25], s[4:5], exec
	s_cselect_b32 s11, s17, s23
	s_cselect_b32 s43, s16, s22
	s_add_u32 s20, s20, 0x80080
	s_addc_u32 s21, s21, 0
	s_add_u32 s44, s22, 0x100
	v_mov_b32_e32 v2, 0
	s_addc_u32 s45, s23, 0
	s_mov_b32 s46, -2
	v_mov_b32_e32 v3, v2
	v_mov_b32_e32 v4, v2
	v_mov_b32_e32 v5, v2
	v_mov_b32_e32 v6, v2
	v_mov_b32_e32 v7, v2
	v_mov_b32_e32 v8, v2
	v_mov_b32_e32 v9, v2
	v_mov_b32_e32 v18, v2
	v_mov_b32_e32 v19, v2
	v_mov_b32_e32 v20, v2
	v_mov_b32_e32 v21, v2
	v_mov_b32_e32 v22, v2
	v_mov_b32_e32 v23, v2
	v_mov_b32_e32 v24, v2
	v_mov_b32_e32 v25, v2
	v_mov_b32_e32 v34, v2
	v_mov_b32_e32 v35, v2
	v_mov_b32_e32 v36, v2
	v_mov_b32_e32 v37, v2
	v_mov_b32_e32 v38, v2
	v_mov_b32_e32 v39, v2
	v_mov_b32_e32 v40, v2
	v_mov_b32_e32 v41, v2
	v_mov_b32_e32 v50, v2
	v_mov_b32_e32 v51, v2
	v_mov_b32_e32 v52, v2
	v_mov_b32_e32 v53, v2
	v_mov_b32_e32 v54, v2
	v_mov_b32_e32 v55, v2
	v_mov_b32_e32 v56, v2
	v_mov_b32_e32 v57, v2
	v_mov_b32_e32 v10, v2
	v_mov_b32_e32 v11, v2
	v_mov_b32_e32 v12, v2
	v_mov_b32_e32 v13, v2
	v_mov_b32_e32 v14, v2
	v_mov_b32_e32 v15, v2
	v_mov_b32_e32 v16, v2
	v_mov_b32_e32 v17, v2
	v_mov_b32_e32 v26, v2
	v_mov_b32_e32 v27, v2
	v_mov_b32_e32 v28, v2
	v_mov_b32_e32 v29, v2
	v_mov_b32_e32 v30, v2
	v_mov_b32_e32 v31, v2
	v_mov_b32_e32 v32, v2
	v_mov_b32_e32 v33, v2
	v_mov_b32_e32 v42, v2
	v_mov_b32_e32 v43, v2
	v_mov_b32_e32 v44, v2
	v_mov_b32_e32 v45, v2
	v_mov_b32_e32 v46, v2
	v_mov_b32_e32 v47, v2
	v_mov_b32_e32 v48, v2
	v_mov_b32_e32 v49, v2
	v_mov_b32_e32 v58, v2
	v_mov_b32_e32 v59, v2
	v_mov_b32_e32 v60, v2
	v_mov_b32_e32 v61, v2
	v_mov_b32_e32 v62, v2
	v_mov_b32_e32 v63, v2
	v_mov_b32_e32 v64, v2
	v_mov_b32_e32 v65, v2
	v_mov_b32_e32 v66, v2
	v_mov_b32_e32 v67, v2
	v_mov_b32_e32 v68, v2
	v_mov_b32_e32 v69, v2
	v_mov_b32_e32 v70, v2
	v_mov_b32_e32 v71, v2
	v_mov_b32_e32 v72, v2
	v_mov_b32_e32 v73, v2
	v_mov_b32_e32 v82, v2
	v_mov_b32_e32 v83, v2
	v_mov_b32_e32 v84, v2
	v_mov_b32_e32 v85, v2
	v_mov_b32_e32 v86, v2
	v_mov_b32_e32 v87, v2
	v_mov_b32_e32 v88, v2
	v_mov_b32_e32 v89, v2
	v_mov_b32_e32 v98, v2
	v_mov_b32_e32 v99, v2
	v_mov_b32_e32 v100, v2
	v_mov_b32_e32 v101, v2
	v_mov_b32_e32 v102, v2
	v_mov_b32_e32 v103, v2
	v_mov_b32_e32 v104, v2
	v_mov_b32_e32 v105, v2
	v_mov_b32_e32 v114, v2
	v_mov_b32_e32 v115, v2
	v_mov_b32_e32 v116, v2
	v_mov_b32_e32 v117, v2
	v_mov_b32_e32 v118, v2
	v_mov_b32_e32 v119, v2
	v_mov_b32_e32 v120, v2
	v_mov_b32_e32 v121, v2
	v_mov_b32_e32 v74, v2
	v_mov_b32_e32 v75, v2
	v_mov_b32_e32 v76, v2
	v_mov_b32_e32 v77, v2
	v_mov_b32_e32 v78, v2
	v_mov_b32_e32 v79, v2
	v_mov_b32_e32 v80, v2
	v_mov_b32_e32 v81, v2
	v_mov_b32_e32 v90, v2
	v_mov_b32_e32 v91, v2
	v_mov_b32_e32 v92, v2
	v_mov_b32_e32 v93, v2
	v_mov_b32_e32 v94, v2
	v_mov_b32_e32 v95, v2
	v_mov_b32_e32 v96, v2
	v_mov_b32_e32 v97, v2
	v_mov_b32_e32 v106, v2
	v_mov_b32_e32 v107, v2
	v_mov_b32_e32 v108, v2
	v_mov_b32_e32 v109, v2
	v_mov_b32_e32 v110, v2
	v_mov_b32_e32 v111, v2
	v_mov_b32_e32 v112, v2
	v_mov_b32_e32 v113, v2
	v_mov_b32_e32 v122, v2
	v_mov_b32_e32 v123, v2
	v_mov_b32_e32 v124, v2
	v_mov_b32_e32 v125, v2
	v_mov_b32_e32 v126, v2
	v_mov_b32_e32 v127, v2
	v_mov_b32_e32 v128, v2
	v_mov_b32_e32 v129, v2
	.p2align 6

; template <class Epi, class Sched, bool ALIGN_EPI = false, bool SP2 = false>
; __device__ __forceinline__ void gemm_phase(PG8_LAS unsigned char* lds, const Gemm g, const Sched& S, const Epi& E) {
;     ...
;             const char* a1 = cA + (size_t)(t + 1) * kstep;
;             const char* a2 = last ? nA : cA + (size_t)(t + 2) * kstep; const char* b2 = last ? nB : cB + (size_t)(t + 2) * kstep;
;             const char* a3 = a2 + kstep; const char* b3 = b2 + kstep;
;     ...
; #pragma unroll
;         for (int a = 0; a < 2; ++a)
; #pragma unroll
;             for (int b = 0; b < 2; ++b)
; #pragma unroll
;                 for (int m = 0; m < 4; ++m)
; #pragma unroll
;                     for (int n = 0; n < 2; ++n) acc[a][b][m][n] = (f32x4){0.f, 0.f, 0.f, 0.f};
.LBB0_2486:
	s_add_u32 s22, s22, 0x160080
	s_addc_u32 s23, s23, 0
	s_add_u32 s51, s24, 0x100
	v_mov_b32_e32 v2, 0
	s_addc_u32 s52, s25, 0
	s_mov_b32 s53, -2
	v_mov_b32_e32 v3, v2
	v_mov_b32_e32 v4, v2
	v_mov_b32_e32 v5, v2
	v_mov_b32_e32 v6, v2
	v_mov_b32_e32 v7, v2
	v_mov_b32_e32 v8, v2
	v_mov_b32_e32 v9, v2
	v_mov_b32_e32 v10, v2
	v_mov_b32_e32 v11, v2
	v_mov_b32_e32 v12, v2
	v_mov_b32_e32 v13, v2
	v_mov_b32_e32 v14, v2
	v_mov_b32_e32 v15, v2
	v_mov_b32_e32 v16, v2
	v_mov_b32_e32 v17, v2
	v_mov_b32_e32 v26, v2
	v_mov_b32_e32 v27, v2
	v_mov_b32_e32 v28, v2
	v_mov_b32_e32 v29, v2
	v_mov_b32_e32 v30, v2
	v_mov_b32_e32 v31, v2
	v_mov_b32_e32 v32, v2
	v_mov_b32_e32 v33, v2
	v_mov_b32_e32 v42, v2
	v_mov_b32_e32 v43, v2
	v_mov_b32_e32 v44, v2
	v_mov_b32_e32 v45, v2
	v_mov_b32_e32 v46, v2
	v_mov_b32_e32 v47, v2
	v_mov_b32_e32 v48, v2
	v_mov_b32_e32 v49, v2
	v_mov_b32_e32 v18, v2
	v_mov_b32_e32 v19, v2
	v_mov_b32_e32 v20, v2
	v_mov_b32_e32 v21, v2
	v_mov_b32_e32 v22, v2
	v_mov_b32_e32 v23, v2
	v_mov_b32_e32 v24, v2
	v_mov_b32_e32 v25, v2
	v_mov_b32_e32 v34, v2
	v_mov_b32_e32 v35, v2
	v_mov_b32_e32 v36, v2
	v_mov_b32_e32 v37, v2
	v_mov_b32_e32 v38, v2
	v_mov_b32_e32 v39, v2
	v_mov_b32_e32 v40, v2
	v_mov_b32_e32 v41, v2
	v_mov_b32_e32 v50, v2
	v_mov_b32_e32 v51, v2
	v_mov_b32_e32 v52, v2
	v_mov_b32_e32 v53, v2
	v_mov_b32_e32 v54, v2
	v_mov_b32_e32 v55, v2
	v_mov_b32_e32 v56, v2
	v_mov_b32_e32 v57, v2
	v_mov_b32_e32 v58, v2
	v_mov_b32_e32 v59, v2
	v_mov_b32_e32 v60, v2
	v_mov_b32_e32 v61, v2
	v_mov_b32_e32 v62, v2
	v_mov_b32_e32 v63, v2
	v_mov_b32_e32 v64, v2
	v_mov_b32_e32 v65, v2
	v_mov_b32_e32 v66, v2
	v_mov_b32_e32 v67, v2
	v_mov_b32_e32 v68, v2
	v_mov_b32_e32 v69, v2
	v_mov_b32_e32 v70, v2
	v_mov_b32_e32 v71, v2
	v_mov_b32_e32 v72, v2
	v_mov_b32_e32 v73, v2
	v_mov_b32_e32 v74, v2
	v_mov_b32_e32 v75, v2
	v_mov_b32_e32 v76, v2
	v_mov_b32_e32 v77, v2
	v_mov_b32_e32 v78, v2
	v_mov_b32_e32 v79, v2
	v_mov_b32_e32 v80, v2
	v_mov_b32_e32 v81, v2
	v_mov_b32_e32 v90, v2
	v_mov_b32_e32 v91, v2
	v_mov_b32_e32 v92, v2
	v_mov_b32_e32 v93, v2
	v_mov_b32_e32 v94, v2
	v_mov_b32_e32 v95, v2
	v_mov_b32_e32 v96, v2
	v_mov_b32_e32 v97, v2
	v_mov_b32_e32 v106, v2
	v_mov_b32_e32 v107, v2
	v_mov_b32_e32 v108, v2
	v_mov_b32_e32 v109, v2
	v_mov_b32_e32 v110, v2
	v_mov_b32_e32 v111, v2
	v_mov_b32_e32 v112, v2
	v_mov_b32_e32 v113, v2
	v_mov_b32_e32 v82, v2
	v_mov_b32_e32 v83, v2
	v_mov_b32_e32 v84, v2
	v_mov_b32_e32 v85, v2
	v_mov_b32_e32 v86, v2
	v_mov_b32_e32 v87, v2
	v_mov_b32_e32 v88, v2
	v_mov_b32_e32 v89, v2
	v_mov_b32_e32 v98, v2
	v_mov_b32_e32 v99, v2
	v_mov_b32_e32 v100, v2
	v_mov_b32_e32 v101, v2
	v_mov_b32_e32 v102, v2
	v_mov_b32_e32 v103, v2
	v_mov_b32_e32 v104, v2
	v_mov_b32_e32 v105, v2
	v_mov_b32_e32 v114, v2
	v_mov_b32_e32 v115, v2
	v_mov_b32_e32 v116, v2
	v_mov_b32_e32 v117, v2
	v_mov_b32_e32 v118, v2
	v_mov_b32_e32 v119, v2
	v_mov_b32_e32 v120, v2
	v_mov_b32_e32 v121, v2
	v_mov_b32_e32 v122, v2
	v_mov_b32_e32 v123, v2
	v_mov_b32_e32 v124, v2
	v_mov_b32_e32 v125, v2
	v_mov_b32_e32 v126, v2
	v_mov_b32_e32 v127, v2
	v_mov_b32_e32 v128, v2
	v_mov_b32_e32 v129, v2
	.p2align 6

; template <class Epi, class Sched, bool ALIGN_EPI = false, bool SP2 = false>
; __device__ __forceinline__ void gemm_phase(PG8_LAS unsigned char* lds, const Gemm g, const Sched& S, const Epi& E) {
;     ...
;         const bool has_next = S.next(ui + 1, nxt);
;         const char* nA = has_next ? (const char*)g.A + (size_t)nxt.pm * tstepA : cA; const char* nB = has_next ? (const char*)g.Bt + (size_t)nxt.pn * tstepB : cB;
;         for (int t = 0; t < nt; t += 2) {
;             const bool last = (t == nt - 2);
;             const char* a1 = cA + (size_t)(t + 1) * kstep;
;             const char* a2 = last ? nA : cA + (size_t)(t + 2) * kstep; const char* b2 = last ? nB : cB + (size_t)(t + 2) * kstep;
;             const char* a3 = a2 + kstep; const char* b3 = b2 + kstep;
;     ...
; #pragma unroll
;         for (int a = 0; a < 2; ++a)
; #pragma unroll
;             for (int b = 0; b < 2; ++b)
; #pragma unroll
;                 for (int m = 0; m < 4; ++m)
; #pragma unroll
;                     for (int n = 0; n < 2; ++n) acc[a][b][m][n] = (f32x4){0.f, 0.f, 0.f, 0.f};
.LBB0_2614:
	s_ashr_i32 s15, s14, 31
	s_lshl_b64 s[16:17], s[14:15], 20
	s_add_u32 s16, s86, s16
	s_addc_u32 s17, s87, s17
	s_and_b64 s[18:19], s[4:5], exec
	s_cselect_b32 s15, s17, s23
	s_cselect_b32 s44, s16, s22
	s_ashr_i32 s13, s12, 31
	s_lshl_b64 s[18:19], s[12:13], 20
	s_add_u32 s18, s62, s18
	s_addc_u32 s19, s63, s19
	s_and_b64 s[26:27], s[4:5], exec
	s_cselect_b32 s13, s19, s25
	s_cselect_b32 s45, s18, s24
	s_add_u32 s22, s22, 0x80080
	s_addc_u32 s23, s23, 0
	s_add_u32 s46, s24, 0x100
	v_mov_b32_e32 v2, 0
	s_addc_u32 s47, s25, 0
	s_mov_b32 s48, -2
	v_mov_b32_e32 v3, v2
	v_mov_b32_e32 v4, v2
	v_mov_b32_e32 v5, v2
	v_mov_b32_e32 v6, v2
	v_mov_b32_e32 v7, v2
	v_mov_b32_e32 v8, v2
	v_mov_b32_e32 v9, v2
	v_mov_b32_e32 v10, v2
	v_mov_b32_e32 v11, v2
	v_mov_b32_e32 v12, v2
	v_mov_b32_e32 v13, v2
	v_mov_b32_e32 v18, v2
	v_mov_b32_e32 v19, v2
	v_mov_b32_e32 v20, v2
	v_mov_b32_e32 v21, v2
	v_mov_b32_e32 v26, v2
	v_mov_b32_e32 v27, v2
	v_mov_b32_e32 v28, v2
	v_mov_b32_e32 v29, v2
	v_mov_b32_e32 v34, v2
	v_mov_b32_e32 v35, v2
	v_mov_b32_e32 v36, v2
	v_mov_b32_e32 v37, v2
	v_mov_b32_e32 v42, v2
	v_mov_b32_e32 v43, v2
	v_mov_b32_e32 v44, v2
	v_mov_b32_e32 v45, v2
	v_mov_b32_e32 v50, v2
	v_mov_b32_e32 v51, v2
	v_mov_b32_e32 v52, v2
	v_mov_b32_e32 v53, v2
	v_mov_b32_e32 v14, v2
	v_mov_b32_e32 v15, v2
	v_mov_b32_e32 v16, v2
	v_mov_b32_e32 v17, v2
	v_mov_b32_e32 v22, v2
	v_mov_b32_e32 v23, v2
	v_mov_b32_e32 v24, v2
	v_mov_b32_e32 v25, v2
	v_mov_b32_e32 v30, v2
	v_mov_b32_e32 v31, v2
	v_mov_b32_e32 v32, v2
	v_mov_b32_e32 v33, v2
	v_mov_b32_e32 v38, v2
	v_mov_b32_e32 v39, v2
	v_mov_b32_e32 v40, v2
	v_mov_b32_e32 v41, v2
	v_mov_b32_e32 v46, v2
	v_mov_b32_e32 v47, v2
	v_mov_b32_e32 v48, v2
	v_mov_b32_e32 v49, v2
	v_mov_b32_e32 v54, v2
	v_mov_b32_e32 v55, v2
	v_mov_b32_e32 v56, v2
	v_mov_b32_e32 v57, v2
	v_mov_b32_e32 v58, v2
	v_mov_b32_e32 v59, v2
	v_mov_b32_e32 v60, v2
	v_mov_b32_e32 v61, v2
	v_mov_b32_e32 v62, v2
	v_mov_b32_e32 v63, v2
	v_mov_b32_e32 v64, v2
	v_mov_b32_e32 v65, v2
	v_mov_b32_e32 v66, v2
	v_mov_b32_e32 v67, v2
	v_mov_b32_e32 v68, v2
	v_mov_b32_e32 v69, v2
	v_mov_b32_e32 v70, v2
	v_mov_b32_e32 v71, v2
	v_mov_b32_e32 v72, v2
	v_mov_b32_e32 v73, v2
	v_mov_b32_e32 v74, v2
	v_mov_b32_e32 v75, v2
	v_mov_b32_e32 v76, v2
	v_mov_b32_e32 v77, v2
	v_mov_b32_e32 v78, v2
	v_mov_b32_e32 v79, v2
	v_mov_b32_e32 v80, v2
	v_mov_b32_e32 v81, v2
	v_mov_b32_e32 v82, v2
	v_mov_b32_e32 v83, v2
	v_mov_b32_e32 v84, v2
	v_mov_b32_e32 v85, v2
	v_mov_b32_e32 v90, v2
	v_mov_b32_e32 v91, v2
	v_mov_b32_e32 v92, v2
	v_mov_b32_e32 v93, v2
	v_mov_b32_e32 v98, v2
	v_mov_b32_e32 v99, v2
	v_mov_b32_e32 v100, v2
	v_mov_b32_e32 v101, v2
	v_mov_b32_e32 v106, v2
	v_mov_b32_e32 v107, v2
	v_mov_b32_e32 v108, v2
	v_mov_b32_e32 v109, v2
	v_mov_b32_e32 v86, v2
	v_mov_b32_e32 v87, v2
	v_mov_b32_e32 v88, v2
	v_mov_b32_e32 v89, v2
	v_mov_b32_e32 v94, v2
	v_mov_b32_e32 v95, v2
	v_mov_b32_e32 v96, v2
	v_mov_b32_e32 v97, v2
	v_mov_b32_e32 v102, v2
	v_mov_b32_e32 v103, v2
	v_mov_b32_e32 v104, v2
	v_mov_b32_e32 v105, v2
	v_mov_b32_e32 v110, v2
	v_mov_b32_e32 v111, v2
	v_mov_b32_e32 v112, v2
	v_mov_b32_e32 v113, v2
	v_mov_b32_e32 v114, v2
	v_mov_b32_e32 v115, v2
	v_mov_b32_e32 v116, v2
	v_mov_b32_e32 v117, v2
	v_mov_b32_e32 v118, v2
	v_mov_b32_e32 v119, v2
	v_mov_b32_e32 v120, v2
	v_mov_b32_e32 v121, v2
	v_mov_b32_e32 v122, v2
	v_mov_b32_e32 v123, v2
	v_mov_b32_e32 v124, v2
	v_mov_b32_e32 v125, v2
	v_mov_b32_e32 v126, v2
	v_mov_b32_e32 v127, v2
	v_mov_b32_e32 v128, v2
	v_mov_b32_e32 v129, v2
	.p2align 6

; template <class Epi, class Sched, bool ALIGN_EPI = false, bool SP2 = false>
; __device__ __forceinline__ void gemm_phase(PG8_LAS unsigned char* lds, const Gemm g, const Sched& S, const Epi& E) {
;     ...
;         const bool has_next = S.next(ui + 1, nxt);
;         const char* nA = has_next ? (const char*)g.A + (size_t)nxt.pm * tstepA : cA; const char* nB = has_next ? (const char*)g.Bt + (size_t)nxt.pn * tstepB : cB;
;         for (int t = 0; t < nt; t += 2) {
;             const bool last = (t == nt - 2);
;             const char* a1 = cA + (size_t)(t + 1) * kstep;
;             const char* a2 = last ? nA : cA + (size_t)(t + 2) * kstep; const char* b2 = last ? nB : cB + (size_t)(t + 2) * kstep;
;             const char* a3 = a2 + kstep; const char* b3 = b2 + kstep;
;     ...
; #pragma unroll
;         for (int a = 0; a < 2; ++a)
; #pragma unroll
;             for (int b = 0; b < 2; ++b)
; #pragma unroll
;                 for (int m = 0; m < 4; ++m)
; #pragma unroll
;                     for (int n = 0; n < 2; ++n) acc[a][b][m][n] = (f32x4){0.f, 0.f, 0.f, 0.f};
.LBB0_3371:
	s_ashr_i32 s23, s22, 31
	s_lshl_b64 s[24:25], s[22:23], 20
	s_add_u32 s24, s86, s24
	s_addc_u32 s25, s87, s25
	s_and_b64 s[26:27], s[4:5], exec
	s_cselect_b32 s23, s25, s31
	s_cselect_b32 s55, s24, s30
	s_ashr_i32 s21, s20, 31
	s_lshl_b64 s[26:27], s[20:21], 20
	s_add_u32 s26, s88, s26
	s_addc_u32 s27, s89, s27
	s_and_b64 s[36:37], s[4:5], exec
	s_cselect_b32 s21, s27, s35
	s_cselect_b32 s56, s26, s34
	s_add_u32 s30, s30, 0x80080
	s_addc_u32 s31, s31, 0
	s_add_u32 s57, s34, 0x100
	v_mov_b32_e32 v2, 0
	s_addc_u32 s58, s35, 0
	s_mov_b32 s59, -2
	v_mov_b32_e32 v3, v2
	v_mov_b32_e32 v4, v2
	v_mov_b32_e32 v5, v2
	v_mov_b32_e32 v6, v2
	v_mov_b32_e32 v7, v2
	v_mov_b32_e32 v8, v2
	v_mov_b32_e32 v9, v2
	v_mov_b32_e32 v10, v2
	v_mov_b32_e32 v11, v2
	v_mov_b32_e32 v12, v2
	v_mov_b32_e32 v13, v2
	v_mov_b32_e32 v18, v2
	v_mov_b32_e32 v19, v2
	v_mov_b32_e32 v20, v2
	v_mov_b32_e32 v21, v2
	v_mov_b32_e32 v26, v2
	v_mov_b32_e32 v27, v2
	v_mov_b32_e32 v28, v2
	v_mov_b32_e32 v29, v2
	v_mov_b32_e32 v34, v2
	v_mov_b32_e32 v35, v2
	v_mov_b32_e32 v36, v2
	v_mov_b32_e32 v37, v2
	v_mov_b32_e32 v42, v2
	v_mov_b32_e32 v43, v2
	v_mov_b32_e32 v44, v2
	v_mov_b32_e32 v45, v2
	v_mov_b32_e32 v50, v2
	v_mov_b32_e32 v51, v2
	v_mov_b32_e32 v52, v2
	v_mov_b32_e32 v53, v2
	v_mov_b32_e32 v14, v2
	v_mov_b32_e32 v15, v2
	v_mov_b32_e32 v16, v2
	v_mov_b32_e32 v17, v2
	v_mov_b32_e32 v22, v2
	v_mov_b32_e32 v23, v2
	v_mov_b32_e32 v24, v2
	v_mov_b32_e32 v25, v2
	v_mov_b32_e32 v30, v2
	v_mov_b32_e32 v31, v2
	v_mov_b32_e32 v32, v2
	v_mov_b32_e32 v33, v2
	v_mov_b32_e32 v38, v2
	v_mov_b32_e32 v39, v2
	v_mov_b32_e32 v40, v2
	v_mov_b32_e32 v41, v2
	v_mov_b32_e32 v46, v2
	v_mov_b32_e32 v47, v2
	v_mov_b32_e32 v48, v2
	v_mov_b32_e32 v49, v2
	v_mov_b32_e32 v54, v2
	v_mov_b32_e32 v55, v2
	v_mov_b32_e32 v56, v2
	v_mov_b32_e32 v57, v2
	v_mov_b32_e32 v58, v2
	v_mov_b32_e32 v59, v2
	v_mov_b32_e32 v60, v2
	v_mov_b32_e32 v61, v2
	v_mov_b32_e32 v62, v2
	v_mov_b32_e32 v63, v2
	v_mov_b32_e32 v64, v2
	v_mov_b32_e32 v65, v2
	v_mov_b32_e32 v66, v2
	v_mov_b32_e32 v67, v2
	v_mov_b32_e32 v68, v2
	v_mov_b32_e32 v69, v2
	v_mov_b32_e32 v70, v2
	v_mov_b32_e32 v71, v2
	v_mov_b32_e32 v72, v2
	v_mov_b32_e32 v73, v2
	v_mov_b32_e32 v74, v2
	v_mov_b32_e32 v75, v2
	v_mov_b32_e32 v76, v2
	v_mov_b32_e32 v77, v2
	v_mov_b32_e32 v78, v2
	v_mov_b32_e32 v79, v2
	v_mov_b32_e32 v80, v2
	v_mov_b32_e32 v81, v2
	v_mov_b32_e32 v82, v2
	v_mov_b32_e32 v83, v2
	v_mov_b32_e32 v84, v2
	v_mov_b32_e32 v85, v2
	v_mov_b32_e32 v90, v2
	v_mov_b32_e32 v91, v2
	v_mov_b32_e32 v92, v2
	v_mov_b32_e32 v93, v2
	v_mov_b32_e32 v98, v2
	v_mov_b32_e32 v99, v2
	v_mov_b32_e32 v100, v2
	v_mov_b32_e32 v101, v2
	v_mov_b32_e32 v106, v2
	v_mov_b32_e32 v107, v2
	v_mov_b32_e32 v108, v2
	v_mov_b32_e32 v109, v2
	v_mov_b32_e32 v86, v2
	v_mov_b32_e32 v87, v2
	v_mov_b32_e32 v88, v2
	v_mov_b32_e32 v89, v2
	v_mov_b32_e32 v94, v2
	v_mov_b32_e32 v95, v2
	v_mov_b32_e32 v96, v2
	v_mov_b32_e32 v97, v2
	v_mov_b32_e32 v102, v2
	v_mov_b32_e32 v103, v2
	v_mov_b32_e32 v104, v2
	v_mov_b32_e32 v105, v2
	v_mov_b32_e32 v110, v2
	v_mov_b32_e32 v111, v2
	v_mov_b32_e32 v112, v2
	v_mov_b32_e32 v113, v2
	v_mov_b32_e32 v114, v2
	v_mov_b32_e32 v115, v2
	v_mov_b32_e32 v116, v2
	v_mov_b32_e32 v117, v2
	v_mov_b32_e32 v118, v2
	v_mov_b32_e32 v119, v2
	v_mov_b32_e32 v120, v2
	v_mov_b32_e32 v121, v2
	v_mov_b32_e32 v122, v2
	v_mov_b32_e32 v123, v2
	v_mov_b32_e32 v124, v2
	v_mov_b32_e32 v125, v2
	v_mov_b32_e32 v126, v2
	v_mov_b32_e32 v127, v2
	v_mov_b32_e32 v128, v2
	v_mov_b32_e32 v129, v2
	.p2align 6

; template <class Epi, class Sched, bool ALIGN_EPI = false, bool SP2 = false>
; __device__ __forceinline__ void gemm_phase(PG8_LAS unsigned char* lds, const Gemm g, const Sched& S, const Epi& E) {
;     ...
;         const bool has_next = S.next(ui + 1, nxt);
;         const char* nA = has_next ? (const char*)g.A + (size_t)nxt.pm * tstepA : cA; const char* nB = has_next ? (const char*)g.Bt + (size_t)nxt.pn * tstepB : cB;
;         for (int t = 0; t < nt; t += 2) {
;             const bool last = (t == nt - 2);
;             const char* a1 = cA + (size_t)(t + 1) * kstep;
;             const char* a2 = last ? nA : cA + (size_t)(t + 2) * kstep; const char* b2 = last ? nB : cB + (size_t)(t + 2) * kstep;
;             const char* a3 = a2 + kstep; const char* b3 = b2 + kstep;
;     ...
; #pragma unroll
;         for (int a = 0; a < 2; ++a)
; #pragma unroll
;             for (int b = 0; b < 2; ++b)
; #pragma unroll
;                 for (int m = 0; m < 4; ++m)
; #pragma unroll
;                     for (int n = 0; n < 2; ++n) acc[a][b][m][n] = (f32x4){0.f, 0.f, 0.f, 0.f};
.LBB0_3499:
	s_ashr_i32 s13, s12, 31
	s_lshl_b64 s[14:15], s[12:13], 20
	s_add_u32 s14, s86, s14
	s_addc_u32 s15, s87, s15
	s_and_b64 s[16:17], s[4:5], exec
	s_cselect_b32 s13, s15, s21
	s_cselect_b32 s44, s14, s20
	s_ashr_i32 s11, s10, 31
	s_lshl_b64 s[16:17], s[10:11], 20
	s_add_u32 s16, s27, s16
	s_addc_u32 s17, s28, s17
	s_and_b64 s[24:25], s[4:5], exec
	s_cselect_b32 s11, s17, s23
	s_cselect_b32 s45, s16, s22
	s_add_u32 s20, s20, 0x80080
	s_addc_u32 s21, s21, 0
	s_add_u32 s46, s22, 0x100
	v_mov_b32_e32 v2, 0
	s_addc_u32 s47, s23, 0
	s_mov_b32 s48, -2
	v_mov_b32_e32 v3, v2
	v_mov_b32_e32 v4, v2
	v_mov_b32_e32 v5, v2
	v_mov_b32_e32 v6, v2
	v_mov_b32_e32 v7, v2
	v_mov_b32_e32 v8, v2
	v_mov_b32_e32 v9, v2
	v_mov_b32_e32 v18, v2
	v_mov_b32_e32 v19, v2
	v_mov_b32_e32 v20, v2
	v_mov_b32_e32 v21, v2
	v_mov_b32_e32 v22, v2
	v_mov_b32_e32 v23, v2
	v_mov_b32_e32 v24, v2
	v_mov_b32_e32 v25, v2
	v_mov_b32_e32 v34, v2
	v_mov_b32_e32 v35, v2
	v_mov_b32_e32 v36, v2
	v_mov_b32_e32 v37, v2
	v_mov_b32_e32 v38, v2
	v_mov_b32_e32 v39, v2
	v_mov_b32_e32 v40, v2
	v_mov_b32_e32 v41, v2
	v_mov_b32_e32 v50, v2
	v_mov_b32_e32 v51, v2
	v_mov_b32_e32 v52, v2
	v_mov_b32_e32 v53, v2
	v_mov_b32_e32 v54, v2
	v_mov_b32_e32 v55, v2
	v_mov_b32_e32 v56, v2
	v_mov_b32_e32 v57, v2
	v_mov_b32_e32 v10, v2
	v_mov_b32_e32 v11, v2
	v_mov_b32_e32 v12, v2
	v_mov_b32_e32 v13, v2
	v_mov_b32_e32 v14, v2
	v_mov_b32_e32 v15, v2
	v_mov_b32_e32 v16, v2
	v_mov_b32_e32 v17, v2
	v_mov_b32_e32 v26, v2
	v_mov_b32_e32 v27, v2
	v_mov_b32_e32 v28, v2
	v_mov_b32_e32 v29, v2
	v_mov_b32_e32 v30, v2
	v_mov_b32_e32 v31, v2
	v_mov_b32_e32 v32, v2
	v_mov_b32_e32 v33, v2
	v_mov_b32_e32 v42, v2
	v_mov_b32_e32 v43, v2
	v_mov_b32_e32 v44, v2
	v_mov_b32_e32 v45, v2
	v_mov_b32_e32 v46, v2
	v_mov_b32_e32 v47, v2
	v_mov_b32_e32 v48, v2
	v_mov_b32_e32 v49, v2
	v_mov_b32_e32 v58, v2
	v_mov_b32_e32 v59, v2
	v_mov_b32_e32 v60, v2
	v_mov_b32_e32 v61, v2
	v_mov_b32_e32 v62, v2
	v_mov_b32_e32 v63, v2
	v_mov_b32_e32 v64, v2
	v_mov_b32_e32 v65, v2
	v_mov_b32_e32 v66, v2
	v_mov_b32_e32 v67, v2
	v_mov_b32_e32 v68, v2
	v_mov_b32_e32 v69, v2
	v_mov_b32_e32 v70, v2
	v_mov_b32_e32 v71, v2
	v_mov_b32_e32 v72, v2
	v_mov_b32_e32 v73, v2
	v_mov_b32_e32 v82, v2
	v_mov_b32_e32 v83, v2
	v_mov_b32_e32 v84, v2
	v_mov_b32_e32 v85, v2
	v_mov_b32_e32 v86, v2
	v_mov_b32_e32 v87, v2
	v_mov_b32_e32 v88, v2
	v_mov_b32_e32 v89, v2
	v_mov_b32_e32 v98, v2
	v_mov_b32_e32 v99, v2
	v_mov_b32_e32 v100, v2
	v_mov_b32_e32 v101, v2
	v_mov_b32_e32 v102, v2
	v_mov_b32_e32 v103, v2
	v_mov_b32_e32 v104, v2
	v_mov_b32_e32 v105, v2
	v_mov_b32_e32 v114, v2
	v_mov_b32_e32 v115, v2
	v_mov_b32_e32 v116, v2
	v_mov_b32_e32 v117, v2
	v_mov_b32_e32 v118, v2
	v_mov_b32_e32 v119, v2
	v_mov_b32_e32 v120, v2
	v_mov_b32_e32 v121, v2
	v_mov_b32_e32 v74, v2
	v_mov_b32_e32 v75, v2
	v_mov_b32_e32 v76, v2
	v_mov_b32_e32 v77, v2
	v_mov_b32_e32 v78, v2
	v_mov_b32_e32 v79, v2
	v_mov_b32_e32 v80, v2
	v_mov_b32_e32 v81, v2
	v_mov_b32_e32 v90, v2
	v_mov_b32_e32 v91, v2
	v_mov_b32_e32 v92, v2
	v_mov_b32_e32 v93, v2
	v_mov_b32_e32 v94, v2
	v_mov_b32_e32 v95, v2
	v_mov_b32_e32 v96, v2
	v_mov_b32_e32 v97, v2
	v_mov_b32_e32 v106, v2
	v_mov_b32_e32 v107, v2
	v_mov_b32_e32 v108, v2
	v_mov_b32_e32 v109, v2
	v_mov_b32_e32 v110, v2
	v_mov_b32_e32 v111, v2
	v_mov_b32_e32 v112, v2
	v_mov_b32_e32 v113, v2
	v_mov_b32_e32 v122, v2
	v_mov_b32_e32 v123, v2
	v_mov_b32_e32 v124, v2
	v_mov_b32_e32 v125, v2
	v_mov_b32_e32 v126, v2
	v_mov_b32_e32 v127, v2
	v_mov_b32_e32 v128, v2
	v_mov_b32_e32 v129, v2
	.p2align 6

; template <class Epi, class Sched, bool ALIGN_EPI = false, bool SP2 = false>
; __device__ __forceinline__ void gemm_phase(PG8_LAS unsigned char* lds, const Gemm g, const Sched& S, const Epi& E) {
;     ...
;             const char* a1 = cA + (size_t)(t + 1) * kstep;
;             const char* a2 = last ? nA : cA + (size_t)(t + 2) * kstep; const char* b2 = last ? nB : cB + (size_t)(t + 2) * kstep;
;             const char* a3 = a2 + kstep; const char* b3 = b2 + kstep;
;     ...
; #pragma unroll
;         for (int a = 0; a < 2; ++a)
; #pragma unroll
;             for (int b = 0; b < 2; ++b)
; #pragma unroll
;                 for (int m = 0; m < 4; ++m)
; #pragma unroll
;                     for (int n = 0; n < 2; ++n) acc[a][b][m][n] = (f32x4){0.f, 0.f, 0.f, 0.f};
.LBB0_3570:
	s_add_u32 s22, s22, 0x160080
	s_addc_u32 s23, s23, 0
	s_add_u32 s53, s24, 0x100
	v_mov_b32_e32 v2, 0
	s_addc_u32 s54, s25, 0
	s_mov_b32 s55, -2
	v_mov_b32_e32 v3, v2
	v_mov_b32_e32 v4, v2
	v_mov_b32_e32 v5, v2
	v_mov_b32_e32 v6, v2
	v_mov_b32_e32 v7, v2
	v_mov_b32_e32 v8, v2
	v_mov_b32_e32 v9, v2
	v_mov_b32_e32 v10, v2
	v_mov_b32_e32 v11, v2
	v_mov_b32_e32 v12, v2
	v_mov_b32_e32 v13, v2
	v_mov_b32_e32 v14, v2
	v_mov_b32_e32 v15, v2
	v_mov_b32_e32 v16, v2
	v_mov_b32_e32 v17, v2
	v_mov_b32_e32 v26, v2
	v_mov_b32_e32 v27, v2
	v_mov_b32_e32 v28, v2
	v_mov_b32_e32 v29, v2
	v_mov_b32_e32 v30, v2
	v_mov_b32_e32 v31, v2
	v_mov_b32_e32 v32, v2
	v_mov_b32_e32 v33, v2
	v_mov_b32_e32 v42, v2
	v_mov_b32_e32 v43, v2
	v_mov_b32_e32 v44, v2
	v_mov_b32_e32 v45, v2
	v_mov_b32_e32 v46, v2
	v_mov_b32_e32 v47, v2
	v_mov_b32_e32 v48, v2
	v_mov_b32_e32 v49, v2
	v_mov_b32_e32 v18, v2
	v_mov_b32_e32 v19, v2
	v_mov_b32_e32 v20, v2
	v_mov_b32_e32 v21, v2
	v_mov_b32_e32 v22, v2
	v_mov_b32_e32 v23, v2
	v_mov_b32_e32 v24, v2
	v_mov_b32_e32 v25, v2
	v_mov_b32_e32 v34, v2
	v_mov_b32_e32 v35, v2
	v_mov_b32_e32 v36, v2
	v_mov_b32_e32 v37, v2
	v_mov_b32_e32 v38, v2
	v_mov_b32_e32 v39, v2
	v_mov_b32_e32 v40, v2
	v_mov_b32_e32 v41, v2
	v_mov_b32_e32 v50, v2
	v_mov_b32_e32 v51, v2
	v_mov_b32_e32 v52, v2
	v_mov_b32_e32 v53, v2
	v_mov_b32_e32 v54, v2
	v_mov_b32_e32 v55, v2
	v_mov_b32_e32 v56, v2
	v_mov_b32_e32 v57, v2
	v_mov_b32_e32 v58, v2
	v_mov_b32_e32 v59, v2
	v_mov_b32_e32 v60, v2
	v_mov_b32_e32 v61, v2
	v_mov_b32_e32 v62, v2
	v_mov_b32_e32 v63, v2
	v_mov_b32_e32 v64, v2
	v_mov_b32_e32 v65, v2
	v_mov_b32_e32 v66, v2
	v_mov_b32_e32 v67, v2
	v_mov_b32_e32 v68, v2
	v_mov_b32_e32 v69, v2
	v_mov_b32_e32 v70, v2
	v_mov_b32_e32 v71, v2
	v_mov_b32_e32 v72, v2
	v_mov_b32_e32 v73, v2
	v_mov_b32_e32 v74, v2
	v_mov_b32_e32 v75, v2
	v_mov_b32_e32 v76, v2
	v_mov_b32_e32 v77, v2
	v_mov_b32_e32 v78, v2
	v_mov_b32_e32 v79, v2
	v_mov_b32_e32 v80, v2
	v_mov_b32_e32 v81, v2
	v_mov_b32_e32 v90, v2
	v_mov_b32_e32 v91, v2
	v_mov_b32_e32 v92, v2
	v_mov_b32_e32 v93, v2
	v_mov_b32_e32 v94, v2
	v_mov_b32_e32 v95, v2
	v_mov_b32_e32 v96, v2
	v_mov_b32_e32 v97, v2
	v_mov_b32_e32 v106, v2
	v_mov_b32_e32 v107, v2
	v_mov_b32_e32 v108, v2
	v_mov_b32_e32 v109, v2
	v_mov_b32_e32 v110, v2
	v_mov_b32_e32 v111, v2
	v_mov_b32_e32 v112, v2
	v_mov_b32_e32 v113, v2
	v_mov_b32_e32 v82, v2
	v_mov_b32_e32 v83, v2
	v_mov_b32_e32 v84, v2
	v_mov_b32_e32 v85, v2
	v_mov_b32_e32 v86, v2
	v_mov_b32_e32 v87, v2
	v_mov_b32_e32 v88, v2
	v_mov_b32_e32 v89, v2
	v_mov_b32_e32 v98, v2
	v_mov_b32_e32 v99, v2
	v_mov_b32_e32 v100, v2
	v_mov_b32_e32 v101, v2
	v_mov_b32_e32 v102, v2
	v_mov_b32_e32 v103, v2
	v_mov_b32_e32 v104, v2
	v_mov_b32_e32 v105, v2
	v_mov_b32_e32 v114, v2
	v_mov_b32_e32 v115, v2
	v_mov_b32_e32 v116, v2
	v_mov_b32_e32 v117, v2
	v_mov_b32_e32 v118, v2
	v_mov_b32_e32 v119, v2
	v_mov_b32_e32 v120, v2
	v_mov_b32_e32 v121, v2
	v_mov_b32_e32 v122, v2
	v_mov_b32_e32 v123, v2
	v_mov_b32_e32 v124, v2
	v_mov_b32_e32 v125, v2
	v_mov_b32_e32 v126, v2
	v_mov_b32_e32 v127, v2
	v_mov_b32_e32 v128, v2
	v_mov_b32_e32 v129, v2
	.p2align 6
